# v6 + static priority variant none (waves 0-3 raised / no priority at all), per-block flips removed
# baseline (speedup 1.0000x reference)
; #define PG8_STAGE(bufoff, gbase, voff) do { _Pragma("unroll") for (int _i = 0; _i < 2; ++_i) \
;         __builtin_amdgcn_global_load_lds((const unsigned*)((const char*)(gbase) + (voff)[_i]), (LAS unsigned*)(lds + (bufoff) + ldsw + _i * 8192), 16, 0, 0); } while (0)
; #define PG8_LDA(dst, b, h) do { _Pragma("unroll") for (int m = 0; m < 4; ++m) _Pragma("unroll") for (int k = 0; k < 2; ++k) dst[m][k] = *(const LAS bf16x8*)(lds + PG8_SA(b, h) + aoff + m * 2048 + k * 1024); } while (0)
; #define PG8_LDB(dst, b, h) do { _Pragma("unroll") for (int n = 0; n < 2; ++n) _Pragma("unroll") for (int k = 0; k < 2; ++k) dst[n][k] = *(const LAS bf16x8*)(lds + PG8_SB(b, h) + boff + n * 2048 + k * 1024); } while (0)
; #define PG8_MMA(ai, bj, At, Bt) do { __builtin_amdgcn_s_setprio(1); _Pragma("unroll") for (int m = 0; m < 4; ++m) _Pragma("unroll") for (int n = 0; n < 2; ++n) _Pragma("unroll") for (int k = 0; k < 2; ++k) \
;         acc[ai][bj][m][n] = __builtin_amdgcn_mfma_f32_16x16x32_bf16(Bt[n][k], At[m][k], acc[ai][bj][m][n], 0, 0, 0); __builtin_amdgcn_s_setprio(0); } while (0)
; #define PG8_WAIT_V(n) asm volatile("s_waitcnt vmcnt(" #n ")" ::: "memory")
; #define PG8_WAIT_L(n) asm volatile("s_waitcnt lgkmcnt(" #n ")" ::: "memory")
; #define PG8_BAR __builtin_amdgcn_s_barrier()
; template <class Epi, class Ptrs>
; __device__ __forceinline__ void gemm_phase(LAS unsigned char* lds, const int K, const StaticOrder& S, const Ptrs& P, const Epi& E) {
;     ...
;             const bool last = (t == nt - 2);
;             const char* a1 = cA + (size_t)(t + 1) * kstep;
;             const char* a2 = last ? nA : cA + (size_t)(t + 2) * kstep; const char* b2 = last ? nB : cB + (size_t)(t + 2) * kstep;
;             const char* a3 = a2 + kstep; const char* b3 = b2 + kstep;
;             PG8_LDB(B0, 0, 0); PG8_SCHED; PG8_LDA(At, 0, 0); PG8_STAGE(PG8_SA(1, 1), a1 + hstep, voffA);
;             PG8_WAIT_L(8); PG8_BAR; PG8_WAIT_L(0); PG8_MMA(0, 0, At, B0); PG8_BAR; PG8_SCHED;
;             PG8_LDB(B1, 0, 1); PG8_STAGE(PG8_SB(0, 0), b2, voffB);
;             PG8_BAR; PG8_WAIT_L(0); PG8_MMA(0, 1, At, B1); PG8_BAR;
;             PG8_LDA(At, 0, 1); PG8_STAGE(PG8_SA(0, 0), a2, voffA);
;             PG8_BAR; PG8_WAIT_L(0); PG8_MMA(1, 0, At, B0); PG8_BAR; PG8_SCHED;
;             PG8_STAGE(PG8_SB(0, 1), b2 + hstep, voffB);
;             PG8_WAIT_V(6); PG8_BAR; PG8_MMA(1, 1, At, B1); PG8_BAR;
.LBB0_127:
	ds_read_b128 v[150:153], v205
	ds_read_b128 v[154:157], v205 offset:1024
	ds_read_b128 v[158:161], v205 offset:2048
	ds_read_b128 v[162:165], v205 offset:3072
	s_add_u32 s69, s6, 0xfffc0080
	s_addc_u32 s71, s7, -1
	s_cmp_eq_u32 s63, 12
	s_cselect_b32 s81, s1, s71
	s_cselect_b32 s80, s0, s69
	s_cselect_b32 s79, s73, s25
	s_cselect_b32 s78, s72, s20
	s_add_i32 m0, s67, 0xc000
	ds_read_b128 v[166:169], v206
	ds_read_b128 v[170:173], v206 offset:1024
	ds_read_b128 v[174:177], v206 offset:2048
	ds_read_b128 v[178:181], v206 offset:3072
	ds_read_b128 v[182:185], v206 offset:4096
	ds_read_b128 v[186:189], v206 offset:5120
	ds_read_b128 v[190:193], v206 offset:6144
	ds_read_b128 v[194:197], v206 offset:7168
	global_load_lds_dwordx4 v142, s[6:7]
	s_add_i32 m0, s67, 0xe000
	s_nop 0
	global_load_lds_dwordx4 v144, s[6:7]
	s_waitcnt lgkmcnt(8)
	s_barrier
	s_waitcnt lgkmcnt(0)
	s_waitcnt lgkmcnt(0)
	v_mfma_f32_16x16x32_bf16 v[120:123], v[150:153], v[166:169], v[120:123]
	v_mfma_f32_16x16x32_bf16 v[120:123], v[154:157], v[170:173], v[120:123]
	v_mfma_f32_16x16x32_bf16 v[116:119], v[162:165], v[170:173], v[116:119]
	v_mfma_f32_16x16x32_bf16 v[116:119], v[158:161], v[166:169], v[116:119]
	v_mfma_f32_16x16x32_bf16 v[100:103], v[158:161], v[174:177], v[100:103]
	v_mfma_f32_16x16x32_bf16 v[100:103], v[162:165], v[178:181], v[100:103]
	v_mfma_f32_16x16x32_bf16 v[104:107], v[154:157], v[178:181], v[104:107]
	v_mfma_f32_16x16x32_bf16 v[104:107], v[150:153], v[174:177], v[104:107]
	v_mfma_f32_16x16x32_bf16 v[88:91], v[150:153], v[182:185], v[88:91]
	v_mfma_f32_16x16x32_bf16 v[88:91], v[154:157], v[186:189], v[88:91]
	v_mfma_f32_16x16x32_bf16 v[84:87], v[162:165], v[186:189], v[84:87]
	v_mfma_f32_16x16x32_bf16 v[84:87], v[158:161], v[182:185], v[84:87]
	v_mfma_f32_16x16x32_bf16 v[68:71], v[158:161], v[190:193], v[68:71]
	v_mfma_f32_16x16x32_bf16 v[68:71], v[162:165], v[194:197], v[68:71]
	v_mfma_f32_16x16x32_bf16 v[72:75], v[154:157], v[194:197], v[72:75]
	v_mfma_f32_16x16x32_bf16 v[72:75], v[150:153], v[190:193], v[72:75]
	s_barrier
	s_add_i32 s69, s91, s65
	v_lshl_add_u64 v[202:203], s[78:79], 0, v[134:135]
	s_mov_b32 m0, s69
	ds_read_b128 v[198:201], v207
	ds_read_b128 v[210:213], v207 offset:1024
	ds_read_b128 v[214:217], v207 offset:2048
	ds_read_b128 v[218:221], v207 offset:3072
	global_load_lds_dwordx4 v[202:203], off
	v_lshl_add_u64 v[222:223], s[78:79], 0, v[138:139]
	s_add_i32 m0, s69, 0x2000
	s_nop 0
	global_load_lds_dwordx4 v[222:223], off
	s_barrier
	s_waitcnt lgkmcnt(0)
	s_waitcnt lgkmcnt(0)
	v_mfma_f32_16x16x32_bf16 v[124:127], v[198:201], v[166:169], v[124:127]
	v_mfma_f32_16x16x32_bf16 v[124:127], v[210:213], v[170:173], v[124:127]
	v_mfma_f32_16x16x32_bf16 v[112:115], v[218:221], v[170:173], v[112:115]
	v_mfma_f32_16x16x32_bf16 v[112:115], v[214:217], v[166:169], v[112:115]
	v_mfma_f32_16x16x32_bf16 v[96:99], v[214:217], v[174:177], v[96:99]
	v_mfma_f32_16x16x32_bf16 v[96:99], v[218:221], v[178:181], v[96:99]
	v_mfma_f32_16x16x32_bf16 v[108:111], v[210:213], v[178:181], v[108:111]
	v_mfma_f32_16x16x32_bf16 v[108:111], v[198:201], v[174:177], v[108:111]
	v_mfma_f32_16x16x32_bf16 v[92:95], v[198:201], v[182:185], v[92:95]
	v_mfma_f32_16x16x32_bf16 v[92:95], v[210:213], v[186:189], v[92:95]
	v_mfma_f32_16x16x32_bf16 v[80:83], v[218:221], v[186:189], v[80:83]
	v_mfma_f32_16x16x32_bf16 v[80:83], v[214:217], v[182:185], v[80:83]
	v_mfma_f32_16x16x32_bf16 v[64:67], v[214:217], v[190:193], v[64:67]
	v_mfma_f32_16x16x32_bf16 v[64:67], v[218:221], v[194:197], v[64:67]
	v_mfma_f32_16x16x32_bf16 v[76:79], v[210:213], v[194:197], v[76:79]
	v_mfma_f32_16x16x32_bf16 v[76:79], v[198:201], v[190:193], v[76:79]
	s_mov_b32 m0, s67
	v_lshl_add_u64 v[224:225], s[80:81], 0, v[132:133]
	s_barrier
	ds_read_b128 v[166:169], v206 offset:16384
	ds_read_b128 v[170:173], v206 offset:17408
	ds_read_b128 v[174:177], v206 offset:18432
	ds_read_b128 v[178:181], v206 offset:19456
	ds_read_b128 v[182:185], v206 offset:20480
	ds_read_b128 v[186:189], v206 offset:21504
	ds_read_b128 v[190:193], v206 offset:22528
	ds_read_b128 v[194:197], v206 offset:23552
	global_load_lds_dwordx4 v[224:225], off
	v_lshl_add_u64 v[226:227], s[80:81], 0, v[136:137]
	s_mov_b32 m0, s75
	s_nop 0
	global_load_lds_dwordx4 v[226:227], off
	s_barrier
	s_waitcnt lgkmcnt(0)
	s_waitcnt lgkmcnt(0)
	v_mfma_f32_16x16x32_bf16 v[56:59], v[150:153], v[166:169], v[56:59]
	v_mfma_f32_16x16x32_bf16 v[56:59], v[154:157], v[170:173], v[56:59]
	v_mfma_f32_16x16x32_bf16 v[52:55], v[162:165], v[170:173], v[52:55]
	v_mfma_f32_16x16x32_bf16 v[52:55], v[158:161], v[166:169], v[52:55]
	v_mfma_f32_16x16x32_bf16 v[36:39], v[158:161], v[174:177], v[36:39]
	v_mfma_f32_16x16x32_bf16 v[36:39], v[162:165], v[178:181], v[36:39]
	v_mfma_f32_16x16x32_bf16 v[40:43], v[154:157], v[178:181], v[40:43]
	v_mfma_f32_16x16x32_bf16 v[40:43], v[150:153], v[174:177], v[40:43]
	v_mfma_f32_16x16x32_bf16 v[24:27], v[150:153], v[182:185], v[24:27]
	v_mfma_f32_16x16x32_bf16 v[24:27], v[154:157], v[186:189], v[24:27]
	v_mfma_f32_16x16x32_bf16 v[20:23], v[162:165], v[186:189], v[20:23]
	v_mfma_f32_16x16x32_bf16 v[20:23], v[158:161], v[182:185], v[20:23]
	v_mfma_f32_16x16x32_bf16 v[4:7], v[158:161], v[190:193], v[4:7]
	v_mfma_f32_16x16x32_bf16 v[4:7], v[162:165], v[194:197], v[4:7]
	v_mfma_f32_16x16x32_bf16 v[8:11], v[154:157], v[194:197], v[8:11]
	v_mfma_f32_16x16x32_bf16 v[8:11], v[150:153], v[190:193], v[8:11]
	s_barrier
	s_add_u32 s82, s78, 0x40000
	s_addc_u32 s83, s79, 0
	s_add_i32 s69, s92, s65
	s_mov_b32 m0, s69
	s_nop 0
	global_load_lds_dwordx4 v134, s[82:83]
	s_add_i32 m0, s69, 0x2000
	s_nop 0
	global_load_lds_dwordx4 v138, s[82:83]
	s_waitcnt vmcnt(6)
	s_barrier
; #define PG8_STAGE(bufoff, gbase, voff) do { _Pragma("unroll") for (int _i = 0; _i < 2; ++_i) \
;         __builtin_amdgcn_global_load_lds((const unsigned*)((const char*)(gbase) + (voff)[_i]), (LAS unsigned*)(lds + (bufoff) + ldsw + _i * 8192), 16, 0, 0); } while (0)
; #define PG8_LDA(dst, b, h) do { _Pragma("unroll") for (int m = 0; m < 4; ++m) _Pragma("unroll") for (int k = 0; k < 2; ++k) dst[m][k] = *(const LAS bf16x8*)(lds + PG8_SA(b, h) + aoff + m * 2048 + k * 1024); } while (0)
; #define PG8_LDB(dst, b, h) do { _Pragma("unroll") for (int n = 0; n < 2; ++n) _Pragma("unroll") for (int k = 0; k < 2; ++k) dst[n][k] = *(const LAS bf16x8*)(lds + PG8_SB(b, h) + boff + n * 2048 + k * 1024); } while (0)
; #define PG8_MMA(ai, bj, At, Bt) do { __builtin_amdgcn_s_setprio(1); _Pragma("unroll") for (int m = 0; m < 4; ++m) _Pragma("unroll") for (int n = 0; n < 2; ++n) _Pragma("unroll") for (int k = 0; k < 2; ++k) \
;         acc[ai][bj][m][n] = __builtin_amdgcn_mfma_f32_16x16x32_bf16(Bt[n][k], At[m][k], acc[ai][bj][m][n], 0, 0, 0); __builtin_amdgcn_s_setprio(0); } while (0)
; #define PG8_WAIT_V(n) asm volatile("s_waitcnt vmcnt(" #n ")" ::: "memory")
; #define PG8_WAIT_L(n) asm volatile("s_waitcnt lgkmcnt(" #n ")" ::: "memory")
; #define PG8_BAR __builtin_amdgcn_s_barrier()
; #define PG8_SCHED __builtin_amdgcn_sched_barrier(0)
; template <class Epi, class Ptrs>
; __device__ __forceinline__ void gemm_phase(LAS unsigned char* lds, const int K, const StaticOrder& S, const Ptrs& P, const Epi& E) {
;     ...
;             PG8_WAIT_V(6); PG8_BAR; PG8_MMA(1, 1, At, B1); PG8_BAR;
;             PG8_LDB(B0, 1, 0); PG8_SCHED; PG8_LDA(At, 1, 0); PG8_STAGE(PG8_SA(0, 1), a2 + hstep, voffA);
;             PG8_WAIT_L(8); PG8_BAR; PG8_WAIT_L(0); PG8_MMA(0, 0, At, B0); PG8_BAR; PG8_SCHED;
;             PG8_LDB(B1, 1, 1); PG8_STAGE(PG8_SB(1, 0), b3, voffB);
;             PG8_BAR; PG8_WAIT_L(0); PG8_MMA(0, 1, At, B1); PG8_BAR;
;             PG8_LDA(At, 1, 1); PG8_STAGE(PG8_SA(1, 0), a3, voffA);
;             PG8_BAR; PG8_WAIT_L(0); PG8_MMA(1, 0, At, B0); PG8_BAR; PG8_SCHED;
	v_mfma_f32_16x16x32_bf16 v[60:63], v[198:201], v[166:169], v[60:63]
	v_mfma_f32_16x16x32_bf16 v[60:63], v[210:213], v[170:173], v[60:63]
	v_mfma_f32_16x16x32_bf16 v[48:51], v[218:221], v[170:173], v[48:51]
	v_mfma_f32_16x16x32_bf16 v[48:51], v[214:217], v[166:169], v[48:51]
	v_mfma_f32_16x16x32_bf16 v[32:35], v[214:217], v[174:177], v[32:35]
	v_mfma_f32_16x16x32_bf16 v[32:35], v[218:221], v[178:181], v[32:35]
	v_mfma_f32_16x16x32_bf16 v[44:47], v[210:213], v[178:181], v[44:47]
	v_mfma_f32_16x16x32_bf16 v[44:47], v[198:201], v[174:177], v[44:47]
	v_mfma_f32_16x16x32_bf16 v[28:31], v[198:201], v[182:185], v[28:31]
	v_mfma_f32_16x16x32_bf16 v[28:31], v[210:213], v[186:189], v[28:31]
	v_mfma_f32_16x16x32_bf16 v[16:19], v[218:221], v[186:189], v[16:19]
	v_mfma_f32_16x16x32_bf16 v[16:19], v[214:217], v[182:185], v[16:19]
	v_mfma_f32_16x16x32_bf16 v[0:3], v[214:217], v[190:193], v[0:3]
	v_mfma_f32_16x16x32_bf16 v[0:3], v[218:221], v[194:197], v[0:3]
	v_mfma_f32_16x16x32_bf16 v[12:15], v[210:213], v[194:197], v[12:15]
	v_mfma_f32_16x16x32_bf16 v[12:15], v[198:201], v[190:193], v[12:15]
	s_add_i32 s69, 0, 0x18000
	v_add_u32_e32 v140, s69, v131
	s_barrier
	ds_read_b128 v[150:153], v140
	ds_read_b128 v[154:157], v140 offset:1024
	ds_read_b128 v[158:161], v140 offset:2048
	ds_read_b128 v[162:165], v140 offset:3072
	s_add_u32 s80, s80, 0x40000
	s_addc_u32 s81, s81, 0
	s_mov_b32 m0, s77
	ds_read_b128 v[166:169], v206 offset:32768
	ds_read_b128 v[170:173], v206 offset:33792
	ds_read_b128 v[174:177], v206 offset:34816
	ds_read_b128 v[178:181], v206 offset:35840
	ds_read_b128 v[182:185], v206 offset:36864
	ds_read_b128 v[186:189], v206 offset:37888
	ds_read_b128 v[190:193], v206 offset:38912
	ds_read_b128 v[194:197], v206 offset:39936
	global_load_lds_dwordx4 v132, s[80:81]
	s_mov_b32 m0, s85
	s_nop 0
	global_load_lds_dwordx4 v136, s[80:81]
	s_waitcnt lgkmcnt(8)
	s_barrier
	s_waitcnt lgkmcnt(0)
	s_waitcnt lgkmcnt(0)
	v_mfma_f32_16x16x32_bf16 v[120:123], v[150:153], v[166:169], v[120:123]
	v_mfma_f32_16x16x32_bf16 v[120:123], v[154:157], v[170:173], v[120:123]
	v_mfma_f32_16x16x32_bf16 v[116:119], v[162:165], v[170:173], v[116:119]
	v_mfma_f32_16x16x32_bf16 v[116:119], v[158:161], v[166:169], v[116:119]
	v_mfma_f32_16x16x32_bf16 v[100:103], v[158:161], v[174:177], v[100:103]
	v_mfma_f32_16x16x32_bf16 v[100:103], v[162:165], v[178:181], v[100:103]
	v_mfma_f32_16x16x32_bf16 v[104:107], v[154:157], v[178:181], v[104:107]
	v_mfma_f32_16x16x32_bf16 v[104:107], v[150:153], v[174:177], v[104:107]
	v_mfma_f32_16x16x32_bf16 v[88:91], v[150:153], v[182:185], v[88:91]
	v_mfma_f32_16x16x32_bf16 v[88:91], v[154:157], v[186:189], v[88:91]
	v_mfma_f32_16x16x32_bf16 v[84:87], v[162:165], v[186:189], v[84:87]
	v_mfma_f32_16x16x32_bf16 v[84:87], v[158:161], v[182:185], v[84:87]
	v_mfma_f32_16x16x32_bf16 v[68:71], v[158:161], v[190:193], v[68:71]
	v_mfma_f32_16x16x32_bf16 v[68:71], v[162:165], v[194:197], v[68:71]
	v_mfma_f32_16x16x32_bf16 v[72:75], v[154:157], v[194:197], v[72:75]
	v_mfma_f32_16x16x32_bf16 v[72:75], v[150:153], v[190:193], v[72:75]
	s_barrier
	s_add_i32 s71, 0, 0x1c000
	s_add_i32 s69, s69, s65
	v_add_u32_e32 v140, s71, v131
	v_lshl_add_u64 v[202:203], v[202:203], 0, s[58:59]
	s_mov_b32 m0, s69
	ds_read_b128 v[198:201], v140
	ds_read_b128 v[210:213], v140 offset:1024
	ds_read_b128 v[214:217], v140 offset:2048
	ds_read_b128 v[218:221], v140 offset:3072
	global_load_lds_dwordx4 v[202:203], off
	v_lshl_add_u64 v[202:203], v[222:223], 0, s[58:59]
	s_add_i32 m0, s69, 0x2000
	s_nop 0
	global_load_lds_dwordx4 v[202:203], off
	s_barrier
	s_waitcnt lgkmcnt(0)
	s_waitcnt lgkmcnt(0)
	v_mfma_f32_16x16x32_bf16 v[124:127], v[198:201], v[166:169], v[124:127]
	v_mfma_f32_16x16x32_bf16 v[124:127], v[210:213], v[170:173], v[124:127]
	v_mfma_f32_16x16x32_bf16 v[112:115], v[218:221], v[170:173], v[112:115]
	v_mfma_f32_16x16x32_bf16 v[112:115], v[214:217], v[166:169], v[112:115]
	v_mfma_f32_16x16x32_bf16 v[96:99], v[214:217], v[174:177], v[96:99]
	v_mfma_f32_16x16x32_bf16 v[96:99], v[218:221], v[178:181], v[96:99]
	v_mfma_f32_16x16x32_bf16 v[108:111], v[210:213], v[178:181], v[108:111]
	v_mfma_f32_16x16x32_bf16 v[108:111], v[198:201], v[174:177], v[108:111]
	v_mfma_f32_16x16x32_bf16 v[92:95], v[198:201], v[182:185], v[92:95]
	v_mfma_f32_16x16x32_bf16 v[92:95], v[210:213], v[186:189], v[92:95]
	v_mfma_f32_16x16x32_bf16 v[80:83], v[218:221], v[186:189], v[80:83]
	v_mfma_f32_16x16x32_bf16 v[80:83], v[214:217], v[182:185], v[80:83]
	v_mfma_f32_16x16x32_bf16 v[64:67], v[214:217], v[190:193], v[64:67]
	v_mfma_f32_16x16x32_bf16 v[64:67], v[218:221], v[194:197], v[64:67]
	v_mfma_f32_16x16x32_bf16 v[76:79], v[210:213], v[194:197], v[76:79]
	v_mfma_f32_16x16x32_bf16 v[76:79], v[198:201], v[190:193], v[76:79]
	s_mov_b32 m0, s89
	v_lshl_add_u64 v[202:203], v[224:225], 0, s[58:59]
	s_barrier
; #define PG8_WAIT_V(n) asm volatile("s_waitcnt vmcnt(" #n ")" ::: "memory")
; template <class Epi, class Ptrs>
; __device__ __forceinline__ void gemm_phase(LAS unsigned char* lds, const int K, const StaticOrder& S, const Ptrs& P, const Epi& E) {
;     ...
;             PG8_BAR; PG8_WAIT_L(0); PG8_MMA(0, 1, At, B1); PG8_BAR;
;             PG8_LDA(At, 1, 1); PG8_STAGE(PG8_SA(1, 0), a3, voffA);
;             PG8_BAR; PG8_WAIT_L(0); PG8_MMA(1, 0, At, B0); PG8_BAR; PG8_SCHED;
;             PG8_STAGE(PG8_SB(1, 1), b3 + hstep, voffB);
;             PG8_WAIT_V(6); PG8_BAR; PG8_MMA(1, 1, At, B1); PG8_BAR;
;         }
;     __device__ __forceinline__ void operator()(const f32x4 (&acc)[2][2][4][2], const Unit& u, int ui, int wr, int wc, int fr, int fq) const {
;         const int pn = u.pn;
;         if (pn < 8) {
;             bf16_t* base = (bf16_t*)(ws + WS_U) + (size_t)(u.pm * 256 + wr * 64 + fr) * DM + pn * 128 + wc * 32 + 8 * fq;
; #pragma unroll
;             for (int ai = 0; ai < 2; ++ai)
; #pragma unroll
;                 for (int m = 0; m < 4; ++m) {
;                     const f32x4 g0 = g1_4(acc[ai][0][m][0], acc[ai][1][m][0]), g1 = g1_4(acc[ai][0][m][1], acc[ai][1][m][1]);
;                     *(u32x4*)(base + (size_t)(ai * 128 + m * 16) * DM) = pack8(g0, g1); }
;             return; }
;         if (pn >= 17 && pn < 21) {
;             bf16_t* base = (bf16_t*)(dout + DO_GVT) + (size_t)((pn - 17) * 256 + wr * 64 + fr) * MTOK + u.pm * 256 + wc * 32 + 8 * fq;
;             float* pp = (float*)(ws + WS_PART) + (size_t)(u.pm * 256 + wc * 32 + 8 * fq) * 8 + (pn - 17) * 2 + wr;
; #pragma unroll
;             for (int bj = 0; bj < 2; ++bj) { f32x4 sq0 = {0.f, 0.f, 0.f, 0.f}, sq1 = {0.f, 0.f, 0.f, 0.f};
; #pragma unroll
;                 for (int ai = 0; ai < 2; ++ai)
; #pragma unroll
;                     for (int m = 0; m < 4; ++m) { const f32x4 g0 = gelu4(acc[ai][bj][m][0]), g1 = gelu4(acc[ai][bj][m][1]);
;                         sq0 += g0 * g0; sq1 += g1 * g1;
;                         *(u32x4*)(base + (size_t)(ai * 128 + m * 16) * MTOK + bj * 128) = pack8(g0, g1); }
; #pragma unroll
;                 for (int j = 0; j < 4; ++j) { const float t0 = row16_sum(sq0[j]), t1 = row16_sum(sq1[j]); if (fr == 0) { pp[(size_t)(bj * 128 + j) * 8] = t0; pp[(size_t)(bj * 128 + 4 + j) * 8] = t1; } } }
;             return; }
;         bf16_t* base; size_t ld; int row0, col0, act;
	ds_read_b128 v[166:169], v206 offset:49152
	ds_read_b128 v[170:173], v206 offset:50176
	ds_read_b128 v[174:177], v206 offset:51200
	ds_read_b128 v[178:181], v206 offset:52224
	ds_read_b128 v[182:185], v206 offset:53248
	ds_read_b128 v[186:189], v206 offset:54272
	ds_read_b128 v[190:193], v206 offset:55296
	ds_read_b128 v[194:197], v206 offset:56320
	global_load_lds_dwordx4 v[202:203], off
	v_lshl_add_u64 v[202:203], v[226:227], 0, s[58:59]
	s_mov_b32 m0, s90
	s_nop 0
	global_load_lds_dwordx4 v[202:203], off
	s_barrier
	s_waitcnt lgkmcnt(0)
	s_waitcnt lgkmcnt(0)
	v_mfma_f32_16x16x32_bf16 v[56:59], v[150:153], v[166:169], v[56:59]
	v_mfma_f32_16x16x32_bf16 v[56:59], v[154:157], v[170:173], v[56:59]
	v_mfma_f32_16x16x32_bf16 v[52:55], v[162:165], v[170:173], v[52:55]
	v_mfma_f32_16x16x32_bf16 v[52:55], v[158:161], v[166:169], v[52:55]
	v_mfma_f32_16x16x32_bf16 v[36:39], v[158:161], v[174:177], v[36:39]
	v_mfma_f32_16x16x32_bf16 v[36:39], v[162:165], v[178:181], v[36:39]
	v_mfma_f32_16x16x32_bf16 v[40:43], v[154:157], v[178:181], v[40:43]
	v_mfma_f32_16x16x32_bf16 v[40:43], v[150:153], v[174:177], v[40:43]
	v_mfma_f32_16x16x32_bf16 v[24:27], v[150:153], v[182:185], v[24:27]
	v_mfma_f32_16x16x32_bf16 v[24:27], v[154:157], v[186:189], v[24:27]
	v_mfma_f32_16x16x32_bf16 v[20:23], v[162:165], v[186:189], v[20:23]
	v_mfma_f32_16x16x32_bf16 v[20:23], v[158:161], v[182:185], v[20:23]
	v_mfma_f32_16x16x32_bf16 v[4:7], v[158:161], v[190:193], v[4:7]
	v_mfma_f32_16x16x32_bf16 v[4:7], v[162:165], v[194:197], v[4:7]
	v_mfma_f32_16x16x32_bf16 v[8:11], v[154:157], v[194:197], v[8:11]
	v_mfma_f32_16x16x32_bf16 v[8:11], v[150:153], v[190:193], v[8:11]
	s_barrier
	s_add_u32 s78, s78, 0x40080
	s_addc_u32 s79, s79, 0
	s_add_i32 s69, s71, s65
	s_mov_b32 m0, s69
	s_nop 0
	global_load_lds_dwordx4 v134, s[78:79]
	s_add_i32 m0, s69, 0x2000
	s_nop 0
	global_load_lds_dwordx4 v138, s[78:79]
	s_waitcnt vmcnt(6)
	s_barrier
	v_mfma_f32_16x16x32_bf16 v[60:63], v[198:201], v[166:169], v[60:63]
	v_mfma_f32_16x16x32_bf16 v[60:63], v[210:213], v[170:173], v[60:63]
	v_mfma_f32_16x16x32_bf16 v[48:51], v[218:221], v[170:173], v[48:51]
	v_mfma_f32_16x16x32_bf16 v[48:51], v[214:217], v[166:169], v[48:51]
	v_mfma_f32_16x16x32_bf16 v[32:35], v[214:217], v[174:177], v[32:35]
	v_mfma_f32_16x16x32_bf16 v[32:35], v[218:221], v[178:181], v[32:35]
	v_mfma_f32_16x16x32_bf16 v[44:47], v[210:213], v[178:181], v[44:47]
	v_mfma_f32_16x16x32_bf16 v[44:47], v[198:201], v[174:177], v[44:47]
	v_mfma_f32_16x16x32_bf16 v[28:31], v[198:201], v[182:185], v[28:31]
	v_mfma_f32_16x16x32_bf16 v[28:31], v[210:213], v[186:189], v[28:31]
	v_mfma_f32_16x16x32_bf16 v[16:19], v[218:221], v[186:189], v[16:19]
	v_mfma_f32_16x16x32_bf16 v[16:19], v[214:217], v[182:185], v[16:19]
	v_mfma_f32_16x16x32_bf16 v[0:3], v[214:217], v[190:193], v[0:3]
	v_mfma_f32_16x16x32_bf16 v[0:3], v[218:221], v[194:197], v[0:3]
	v_mfma_f32_16x16x32_bf16 v[12:15], v[210:213], v[194:197], v[12:15]
	v_mfma_f32_16x16x32_bf16 v[12:15], v[198:201], v[190:193], v[12:15]
	s_add_i32 s63, s63, 2
	s_add_u32 s6, s6, 0x100
	s_addc_u32 s7, s7, 0
	s_add_u32 s20, s20, 0x100
	s_addc_u32 s25, s25, 0
	s_cmp_gt_u32 s63, 13
	s_barrier
	s_cbranch_scc0 .LBB0_127
	s_nop 0
	s_nop 0
	s_nop 0
	s_nop 0
	s_nop 0
	s_nop 0
	s_nop 0
	s_nop 0
	s_nop 0
	s_nop 0
	s_nop 0
	s_nop 0
	s_nop 0
	s_nop 0
	s_nop 0
	s_nop 0
	s_nop 0
	s_nop 0
	s_nop 0
	s_nop 0
	s_nop 0
	s_nop 0
	s_nop 0
	s_nop 0
	s_nop 0
	s_nop 0
	s_nop 0
	s_nop 0
	s_nop 0
	s_nop 0
	s_nop 0
	s_nop 0
	s_cmp_gt_i32 s74, 7
	s_mov_b64 s[6:7], -1
	s_cbranch_scc0 .LBB0_188
	s_sub_i32 s25, s74, 17
	s_cmp_gt_u32 s25, 3
	s_cbranch_scc0 .LBB0_170
	s_lshl_b32 s69, s76, 8
	s_cmp_gt_u32 s74, 11
	s_cbranch_scc0 .LBB0_135
	s_cmp_eq_u32 s74, 12
	s_mov_b64 s[6:7], 0
	s_cbranch_scc1 .LBB0_134
	s_cmp_gt_u32 s74, 16
	s_cbranch_scc1 .LBB0_191
	s_lshl_b32 s20, s74, 8
	v_readlane_b32 s80, v254, 2
	s_addk_i32 s20, 0xf300
	s_mov_b64 s[78:79], 0x400
	s_mov_b64 s[82:83], -1
	s_mov_b32 s63, s69
	v_readlane_b32 s81, v254, 3
	s_andn2_b64 vcc, exec, s[6:7]
	s_cbranch_vccz .LBB0_136
	s_branch .LBB0_137

; #define PG8_STAGE(bufoff, gbase, voff) do { _Pragma("unroll") for (int _i = 0; _i < 2; ++_i) \
;         __builtin_amdgcn_global_load_lds((const unsigned*)((const char*)(gbase) + (voff)[_i]), (LAS unsigned*)(lds + (bufoff) + ldsw + _i * 8192), 16, 0, 0); } while (0)
; #define PG8_LDA(dst, b, h) do { _Pragma("unroll") for (int m = 0; m < 4; ++m) _Pragma("unroll") for (int k = 0; k < 2; ++k) dst[m][k] = *(const LAS bf16x8*)(lds + PG8_SA(b, h) + aoff + m * 2048 + k * 1024); } while (0)
; #define PG8_LDB(dst, b, h) do { _Pragma("unroll") for (int n = 0; n < 2; ++n) _Pragma("unroll") for (int k = 0; k < 2; ++k) dst[n][k] = *(const LAS bf16x8*)(lds + PG8_SB(b, h) + boff + n * 2048 + k * 1024); } while (0)
; #define PG8_MMA(ai, bj, At, Bt) do { __builtin_amdgcn_s_setprio(1); _Pragma("unroll") for (int m = 0; m < 4; ++m) _Pragma("unroll") for (int n = 0; n < 2; ++n) _Pragma("unroll") for (int k = 0; k < 2; ++k) \
;         acc[ai][bj][m][n] = __builtin_amdgcn_mfma_f32_16x16x32_bf16(Bt[n][k], At[m][k], acc[ai][bj][m][n], 0, 0, 0); __builtin_amdgcn_s_setprio(0); } while (0)
; #define PG8_WAIT_V(n) asm volatile("s_waitcnt vmcnt(" #n ")" ::: "memory")
; #define PG8_WAIT_L(n) asm volatile("s_waitcnt lgkmcnt(" #n ")" ::: "memory")
; #define PG8_BAR __builtin_amdgcn_s_barrier()
; template <class Epi, class Ptrs>
; __device__ __forceinline__ void gemm_phase(LAS unsigned char* lds, const int K, const StaticOrder& S, const Ptrs& P, const Epi& E) {
;     ...
;             const bool last = (t == nt - 2);
;             const char* a1 = cA + (size_t)(t + 1) * kstep;
;             const char* a2 = last ? nA : cA + (size_t)(t + 2) * kstep; const char* b2 = last ? nB : cB + (size_t)(t + 2) * kstep;
;             const char* a3 = a2 + kstep; const char* b3 = b2 + kstep;
;             PG8_LDB(B0, 0, 0); PG8_SCHED; PG8_LDA(At, 0, 0); PG8_STAGE(PG8_SA(1, 1), a1 + hstep, voffA);
;             PG8_WAIT_L(8); PG8_BAR; PG8_WAIT_L(0); PG8_MMA(0, 0, At, B0); PG8_BAR; PG8_SCHED;
;             PG8_LDB(B1, 0, 1); PG8_STAGE(PG8_SB(0, 0), b2, voffB);
;             PG8_BAR; PG8_WAIT_L(0); PG8_MMA(0, 1, At, B1); PG8_BAR;
;             PG8_LDA(At, 0, 1); PG8_STAGE(PG8_SA(0, 0), a2, voffA);
;             PG8_BAR; PG8_WAIT_L(0); PG8_MMA(1, 0, At, B0); PG8_BAR; PG8_SCHED;
;             PG8_STAGE(PG8_SB(0, 1), b2 + hstep, voffB);
;             PG8_WAIT_V(6); PG8_BAR; PG8_MMA(1, 1, At, B1); PG8_BAR;
.LBB0_353:
	ds_read_b128 v[128:131], v207
	ds_read_b128 v[132:135], v207 offset:1024
	ds_read_b128 v[136:139], v207 offset:2048
	ds_read_b128 v[140:143], v207 offset:3072
	s_add_u32 s42, s38, 0xfffc0080
	s_addc_u32 s43, s39, -1
	s_cmp_eq_u32 s41, 12
	s_cselect_b32 s45, s1, s43
	s_cselect_b32 s44, s0, s42
	s_cselect_b32 s43, s25, s23
	s_cselect_b32 s42, s24, s21
	s_add_i32 m0, s54, 0xc000
	ds_read_b128 v[144:147], v209
	ds_read_b128 v[148:151], v209 offset:1024
	ds_read_b128 v[152:155], v209 offset:2048
	ds_read_b128 v[156:159], v209 offset:3072
	ds_read_b128 v[160:163], v209 offset:4096
	ds_read_b128 v[164:167], v209 offset:5120
	ds_read_b128 v[168:171], v209 offset:6144
	ds_read_b128 v[172:175], v209 offset:7168
	global_load_lds_dwordx4 v184, s[38:39]
	s_add_i32 m0, s54, 0xe000
	s_nop 0
	global_load_lds_dwordx4 v186, s[38:39]
	s_waitcnt lgkmcnt(8)
	s_barrier
	s_waitcnt lgkmcnt(0)
	s_waitcnt lgkmcnt(0)
	v_mfma_f32_16x16x32_bf16 v[124:127], v[128:131], v[144:147], v[124:127]
	v_mfma_f32_16x16x32_bf16 v[124:127], v[132:135], v[148:151], v[124:127]
	v_mfma_f32_16x16x32_bf16 v[120:123], v[140:143], v[148:151], v[120:123]
	v_mfma_f32_16x16x32_bf16 v[120:123], v[136:139], v[144:147], v[120:123]
	v_mfma_f32_16x16x32_bf16 v[104:107], v[136:139], v[152:155], v[104:107]
	v_mfma_f32_16x16x32_bf16 v[104:107], v[140:143], v[156:159], v[104:107]
	v_mfma_f32_16x16x32_bf16 v[108:111], v[132:135], v[156:159], v[108:111]
	v_mfma_f32_16x16x32_bf16 v[108:111], v[128:131], v[152:155], v[108:111]
	v_mfma_f32_16x16x32_bf16 v[92:95], v[128:131], v[160:163], v[92:95]
	v_mfma_f32_16x16x32_bf16 v[92:95], v[132:135], v[164:167], v[92:95]
	v_mfma_f32_16x16x32_bf16 v[88:91], v[140:143], v[164:167], v[88:91]
	v_mfma_f32_16x16x32_bf16 v[88:91], v[136:139], v[160:163], v[88:91]
	v_mfma_f32_16x16x32_bf16 v[72:75], v[136:139], v[168:171], v[72:75]
	v_mfma_f32_16x16x32_bf16 v[72:75], v[140:143], v[172:175], v[72:75]
	v_mfma_f32_16x16x32_bf16 v[76:79], v[132:135], v[172:175], v[76:79]
	v_mfma_f32_16x16x32_bf16 v[76:79], v[128:131], v[168:171], v[76:79]
	s_barrier
	s_add_i32 s69, s66, s51
	v_lshl_add_u64 v[216:217], s[42:43], 0, v[178:179]
	s_mov_b32 m0, s69
	ds_read_b128 v[192:195], v210
	ds_read_b128 v[196:199], v210 offset:1024
	ds_read_b128 v[200:203], v210 offset:2048
	ds_read_b128 v[212:215], v210 offset:3072
	global_load_lds_dwordx4 v[216:217], off
	v_lshl_add_u64 v[218:219], s[42:43], 0, v[182:183]
	s_add_i32 m0, s69, 0x2000
	s_nop 0
	global_load_lds_dwordx4 v[218:219], off
	s_barrier
	s_waitcnt lgkmcnt(0)
	s_waitcnt lgkmcnt(0)
	v_mfma_f32_16x16x32_bf16 v[116:119], v[192:195], v[144:147], v[116:119]
	v_mfma_f32_16x16x32_bf16 v[116:119], v[196:199], v[148:151], v[116:119]
	v_mfma_f32_16x16x32_bf16 v[112:115], v[212:215], v[148:151], v[112:115]
	v_mfma_f32_16x16x32_bf16 v[112:115], v[200:203], v[144:147], v[112:115]
	v_mfma_f32_16x16x32_bf16 v[96:99], v[200:203], v[152:155], v[96:99]
	v_mfma_f32_16x16x32_bf16 v[96:99], v[212:215], v[156:159], v[96:99]
	v_mfma_f32_16x16x32_bf16 v[100:103], v[196:199], v[156:159], v[100:103]
	v_mfma_f32_16x16x32_bf16 v[100:103], v[192:195], v[152:155], v[100:103]
	v_mfma_f32_16x16x32_bf16 v[84:87], v[192:195], v[160:163], v[84:87]
	v_mfma_f32_16x16x32_bf16 v[84:87], v[196:199], v[164:167], v[84:87]
	v_mfma_f32_16x16x32_bf16 v[80:83], v[212:215], v[164:167], v[80:83]
	v_mfma_f32_16x16x32_bf16 v[80:83], v[200:203], v[160:163], v[80:83]
	v_mfma_f32_16x16x32_bf16 v[64:67], v[200:203], v[168:171], v[64:67]
	v_mfma_f32_16x16x32_bf16 v[64:67], v[212:215], v[172:175], v[64:67]
	v_mfma_f32_16x16x32_bf16 v[68:71], v[196:199], v[172:175], v[68:71]
	v_mfma_f32_16x16x32_bf16 v[68:71], v[192:195], v[168:171], v[68:71]
	s_mov_b32 m0, s54
	v_lshl_add_u64 v[220:221], s[44:45], 0, v[176:177]
	s_barrier
	ds_read_b128 v[144:147], v209 offset:16384
	ds_read_b128 v[148:151], v209 offset:17408
	ds_read_b128 v[152:155], v209 offset:18432
	ds_read_b128 v[156:159], v209 offset:19456
	ds_read_b128 v[160:163], v209 offset:20480
	ds_read_b128 v[164:167], v209 offset:21504
	ds_read_b128 v[168:171], v209 offset:22528
	ds_read_b128 v[172:175], v209 offset:23552
	global_load_lds_dwordx4 v[220:221], off
	v_lshl_add_u64 v[222:223], s[44:45], 0, v[180:181]
	s_mov_b32 m0, s55
	s_nop 0
	global_load_lds_dwordx4 v[222:223], off
	s_barrier
	s_waitcnt lgkmcnt(0)
	s_waitcnt lgkmcnt(0)
	v_mfma_f32_16x16x32_bf16 v[60:63], v[128:131], v[144:147], v[60:63]
	v_mfma_f32_16x16x32_bf16 v[60:63], v[132:135], v[148:151], v[60:63]
	v_mfma_f32_16x16x32_bf16 v[56:59], v[140:143], v[148:151], v[56:59]
	v_mfma_f32_16x16x32_bf16 v[56:59], v[136:139], v[144:147], v[56:59]
	v_mfma_f32_16x16x32_bf16 v[40:43], v[136:139], v[152:155], v[40:43]
	v_mfma_f32_16x16x32_bf16 v[40:43], v[140:143], v[156:159], v[40:43]
	v_mfma_f32_16x16x32_bf16 v[44:47], v[132:135], v[156:159], v[44:47]
	v_mfma_f32_16x16x32_bf16 v[44:47], v[128:131], v[152:155], v[44:47]
	v_mfma_f32_16x16x32_bf16 v[28:31], v[128:131], v[160:163], v[28:31]
	v_mfma_f32_16x16x32_bf16 v[28:31], v[132:135], v[164:167], v[28:31]
	v_mfma_f32_16x16x32_bf16 v[24:27], v[140:143], v[164:167], v[24:27]
	v_mfma_f32_16x16x32_bf16 v[24:27], v[136:139], v[160:163], v[24:27]
	v_mfma_f32_16x16x32_bf16 v[8:11], v[136:139], v[168:171], v[8:11]
	v_mfma_f32_16x16x32_bf16 v[8:11], v[140:143], v[172:175], v[8:11]
	v_mfma_f32_16x16x32_bf16 v[12:15], v[132:135], v[172:175], v[12:15]
	v_mfma_f32_16x16x32_bf16 v[12:15], v[128:131], v[168:171], v[12:15]
	s_barrier
	s_add_u32 s70, s42, 0x40000
	s_addc_u32 s71, s43, 0
	s_add_i32 s69, s67, s51
	s_mov_b32 m0, s69
	s_nop 0
	global_load_lds_dwordx4 v178, s[70:71]
	s_add_i32 m0, s69, 0x2000
	s_nop 0
	global_load_lds_dwordx4 v182, s[70:71]
	s_waitcnt vmcnt(6)
	s_barrier
; #define PG8_STAGE(bufoff, gbase, voff) do { _Pragma("unroll") for (int _i = 0; _i < 2; ++_i) \
;         __builtin_amdgcn_global_load_lds((const unsigned*)((const char*)(gbase) + (voff)[_i]), (LAS unsigned*)(lds + (bufoff) + ldsw + _i * 8192), 16, 0, 0); } while (0)
; #define PG8_LDA(dst, b, h) do { _Pragma("unroll") for (int m = 0; m < 4; ++m) _Pragma("unroll") for (int k = 0; k < 2; ++k) dst[m][k] = *(const LAS bf16x8*)(lds + PG8_SA(b, h) + aoff + m * 2048 + k * 1024); } while (0)
; #define PG8_LDB(dst, b, h) do { _Pragma("unroll") for (int n = 0; n < 2; ++n) _Pragma("unroll") for (int k = 0; k < 2; ++k) dst[n][k] = *(const LAS bf16x8*)(lds + PG8_SB(b, h) + boff + n * 2048 + k * 1024); } while (0)
; #define PG8_MMA(ai, bj, At, Bt) do { __builtin_amdgcn_s_setprio(1); _Pragma("unroll") for (int m = 0; m < 4; ++m) _Pragma("unroll") for (int n = 0; n < 2; ++n) _Pragma("unroll") for (int k = 0; k < 2; ++k) \
;         acc[ai][bj][m][n] = __builtin_amdgcn_mfma_f32_16x16x32_bf16(Bt[n][k], At[m][k], acc[ai][bj][m][n], 0, 0, 0); __builtin_amdgcn_s_setprio(0); } while (0)
; #define PG8_WAIT_V(n) asm volatile("s_waitcnt vmcnt(" #n ")" ::: "memory")
; #define PG8_WAIT_L(n) asm volatile("s_waitcnt lgkmcnt(" #n ")" ::: "memory")
; #define PG8_BAR __builtin_amdgcn_s_barrier()
; #define PG8_SCHED __builtin_amdgcn_sched_barrier(0)
; template <class Epi, class Ptrs>
; __device__ __forceinline__ void gemm_phase(LAS unsigned char* lds, const int K, const StaticOrder& S, const Ptrs& P, const Epi& E) {
;     ...
;             PG8_WAIT_V(6); PG8_BAR; PG8_MMA(1, 1, At, B1); PG8_BAR;
;             PG8_LDB(B0, 1, 0); PG8_SCHED; PG8_LDA(At, 1, 0); PG8_STAGE(PG8_SA(0, 1), a2 + hstep, voffA);
;             PG8_WAIT_L(8); PG8_BAR; PG8_WAIT_L(0); PG8_MMA(0, 0, At, B0); PG8_BAR; PG8_SCHED;
;             PG8_LDB(B1, 1, 1); PG8_STAGE(PG8_SB(1, 0), b3, voffB);
;             PG8_BAR; PG8_WAIT_L(0); PG8_MMA(0, 1, At, B1); PG8_BAR;
;             PG8_LDA(At, 1, 1); PG8_STAGE(PG8_SA(1, 0), a3, voffA);
	v_mfma_f32_16x16x32_bf16 v[52:55], v[192:195], v[144:147], v[52:55]
	v_mfma_f32_16x16x32_bf16 v[52:55], v[196:199], v[148:151], v[52:55]
	v_mfma_f32_16x16x32_bf16 v[48:51], v[212:215], v[148:151], v[48:51]
	v_mfma_f32_16x16x32_bf16 v[48:51], v[200:203], v[144:147], v[48:51]
	v_mfma_f32_16x16x32_bf16 v[32:35], v[200:203], v[152:155], v[32:35]
	v_mfma_f32_16x16x32_bf16 v[32:35], v[212:215], v[156:159], v[32:35]
	v_mfma_f32_16x16x32_bf16 v[36:39], v[196:199], v[156:159], v[36:39]
	v_mfma_f32_16x16x32_bf16 v[36:39], v[192:195], v[152:155], v[36:39]
	v_mfma_f32_16x16x32_bf16 v[20:23], v[192:195], v[160:163], v[20:23]
	v_mfma_f32_16x16x32_bf16 v[20:23], v[196:199], v[164:167], v[20:23]
	v_mfma_f32_16x16x32_bf16 v[16:19], v[212:215], v[164:167], v[16:19]
	v_mfma_f32_16x16x32_bf16 v[16:19], v[200:203], v[160:163], v[16:19]
	v_mfma_f32_16x16x32_bf16 v[0:3], v[200:203], v[168:171], v[0:3]
	v_mfma_f32_16x16x32_bf16 v[0:3], v[212:215], v[172:175], v[0:3]
	v_mfma_f32_16x16x32_bf16 v[4:7], v[196:199], v[172:175], v[4:7]
	v_mfma_f32_16x16x32_bf16 v[4:7], v[192:195], v[168:171], v[4:7]
	s_add_i32 s69, 0, 0x18000
	v_add_u32_e32 v140, s69, v205
	s_barrier
	ds_read_b128 v[128:131], v140
	ds_read_b128 v[132:135], v140 offset:1024
	ds_read_b128 v[136:139], v140 offset:2048
	ds_read_b128 v[140:143], v140 offset:3072
	s_add_u32 s44, s44, 0x40000
	s_addc_u32 s45, s45, 0
	s_mov_b32 m0, s56
	ds_read_b128 v[144:147], v209 offset:32768
	ds_read_b128 v[148:151], v209 offset:33792
	ds_read_b128 v[152:155], v209 offset:34816
	ds_read_b128 v[156:159], v209 offset:35840
	ds_read_b128 v[160:163], v209 offset:36864
	ds_read_b128 v[164:167], v209 offset:37888
	ds_read_b128 v[168:171], v209 offset:38912
	ds_read_b128 v[172:175], v209 offset:39936
	global_load_lds_dwordx4 v176, s[44:45]
	s_mov_b32 m0, s57
	s_nop 0
	global_load_lds_dwordx4 v180, s[44:45]
	s_waitcnt lgkmcnt(8)
	s_barrier
	s_waitcnt lgkmcnt(0)
	s_waitcnt lgkmcnt(0)
	v_mfma_f32_16x16x32_bf16 v[124:127], v[128:131], v[144:147], v[124:127]
	v_mfma_f32_16x16x32_bf16 v[124:127], v[132:135], v[148:151], v[124:127]
	v_mfma_f32_16x16x32_bf16 v[120:123], v[140:143], v[148:151], v[120:123]
	v_mfma_f32_16x16x32_bf16 v[120:123], v[136:139], v[144:147], v[120:123]
	v_mfma_f32_16x16x32_bf16 v[104:107], v[136:139], v[152:155], v[104:107]
	v_mfma_f32_16x16x32_bf16 v[104:107], v[140:143], v[156:159], v[104:107]
	v_mfma_f32_16x16x32_bf16 v[108:111], v[132:135], v[156:159], v[108:111]
	v_mfma_f32_16x16x32_bf16 v[108:111], v[128:131], v[152:155], v[108:111]
	v_mfma_f32_16x16x32_bf16 v[92:95], v[128:131], v[160:163], v[92:95]
	v_mfma_f32_16x16x32_bf16 v[92:95], v[132:135], v[164:167], v[92:95]
	v_mfma_f32_16x16x32_bf16 v[88:91], v[140:143], v[164:167], v[88:91]
	v_mfma_f32_16x16x32_bf16 v[88:91], v[136:139], v[160:163], v[88:91]
	v_mfma_f32_16x16x32_bf16 v[72:75], v[136:139], v[168:171], v[72:75]
	v_mfma_f32_16x16x32_bf16 v[72:75], v[140:143], v[172:175], v[72:75]
	v_mfma_f32_16x16x32_bf16 v[76:79], v[132:135], v[172:175], v[76:79]
	v_mfma_f32_16x16x32_bf16 v[76:79], v[128:131], v[168:171], v[76:79]
	s_barrier
	s_add_i32 s44, 0, 0x1c000
	s_add_i32 s45, s69, s51
	v_add_u32_e32 v211, s44, v205
	v_lshl_add_u64 v[216:217], v[216:217], 0, s[18:19]
	s_mov_b32 m0, s45
	ds_read_b128 v[192:195], v211
	ds_read_b128 v[196:199], v211 offset:1024
	ds_read_b128 v[200:203], v211 offset:2048
	ds_read_b128 v[212:215], v211 offset:3072
	global_load_lds_dwordx4 v[216:217], off
	v_lshl_add_u64 v[216:217], v[218:219], 0, s[18:19]
	s_add_i32 m0, s45, 0x2000
	s_nop 0
	global_load_lds_dwordx4 v[216:217], off
	s_barrier
	s_waitcnt lgkmcnt(0)
	s_waitcnt lgkmcnt(0)
	v_mfma_f32_16x16x32_bf16 v[116:119], v[192:195], v[144:147], v[116:119]
	v_mfma_f32_16x16x32_bf16 v[116:119], v[196:199], v[148:151], v[116:119]
	v_mfma_f32_16x16x32_bf16 v[112:115], v[212:215], v[148:151], v[112:115]
	v_mfma_f32_16x16x32_bf16 v[112:115], v[200:203], v[144:147], v[112:115]
	v_mfma_f32_16x16x32_bf16 v[96:99], v[200:203], v[152:155], v[96:99]
	v_mfma_f32_16x16x32_bf16 v[96:99], v[212:215], v[156:159], v[96:99]
	v_mfma_f32_16x16x32_bf16 v[100:103], v[196:199], v[156:159], v[100:103]
	v_mfma_f32_16x16x32_bf16 v[100:103], v[192:195], v[152:155], v[100:103]
	v_mfma_f32_16x16x32_bf16 v[84:87], v[192:195], v[160:163], v[84:87]
	v_mfma_f32_16x16x32_bf16 v[84:87], v[196:199], v[164:167], v[84:87]
	v_mfma_f32_16x16x32_bf16 v[80:83], v[212:215], v[164:167], v[80:83]
	v_mfma_f32_16x16x32_bf16 v[80:83], v[200:203], v[160:163], v[80:83]
	v_mfma_f32_16x16x32_bf16 v[64:67], v[200:203], v[168:171], v[64:67]
	v_mfma_f32_16x16x32_bf16 v[64:67], v[212:215], v[172:175], v[64:67]
	v_mfma_f32_16x16x32_bf16 v[68:71], v[196:199], v[172:175], v[68:71]
	v_mfma_f32_16x16x32_bf16 v[68:71], v[192:195], v[168:171], v[68:71]
	s_mov_b32 m0, s63
	v_lshl_add_u64 v[216:217], v[220:221], 0, s[18:19]
	s_barrier
	ds_read_b128 v[144:147], v209 offset:49152
	ds_read_b128 v[148:151], v209 offset:50176
	ds_read_b128 v[152:155], v209 offset:51200
	ds_read_b128 v[156:159], v209 offset:52224
	ds_read_b128 v[160:163], v209 offset:53248
	ds_read_b128 v[164:167], v209 offset:54272
	ds_read_b128 v[168:171], v209 offset:55296
	ds_read_b128 v[172:175], v209 offset:56320
	global_load_lds_dwordx4 v[216:217], off
	v_lshl_add_u64 v[216:217], v[222:223], 0, s[18:19]
	s_mov_b32 m0, s64
	s_nop 0
	global_load_lds_dwordx4 v[216:217], off
	s_barrier
; #define PG8_STAGE(bufoff, gbase, voff) do { _Pragma("unroll") for (int _i = 0; _i < 2; ++_i) \
;         __builtin_amdgcn_global_load_lds((const unsigned*)((const char*)(gbase) + (voff)[_i]), (LAS unsigned*)(lds + (bufoff) + ldsw + _i * 8192), 16, 0, 0); } while (0)
; #define PG8_MMA(ai, bj, At, Bt) do { __builtin_amdgcn_s_setprio(1); _Pragma("unroll") for (int m = 0; m < 4; ++m) _Pragma("unroll") for (int n = 0; n < 2; ++n) _Pragma("unroll") for (int k = 0; k < 2; ++k) \
;         acc[ai][bj][m][n] = __builtin_amdgcn_mfma_f32_16x16x32_bf16(Bt[n][k], At[m][k], acc[ai][bj][m][n], 0, 0, 0); __builtin_amdgcn_s_setprio(0); } while (0)
; #define PG8_WAIT_V(n) asm volatile("s_waitcnt vmcnt(" #n ")" ::: "memory")
; #define PG8_WAIT_L(n) asm volatile("s_waitcnt lgkmcnt(" #n ")" ::: "memory")
; #define PG8_BAR __builtin_amdgcn_s_barrier()
; #define PG8_SCHED __builtin_amdgcn_sched_barrier(0)
; template <class Epi, class Ptrs>
; __device__ __forceinline__ void gemm_phase(LAS unsigned char* lds, const int K, const StaticOrder& S, const Ptrs& P, const Epi& E) {
;     ...
;             PG8_BAR; PG8_WAIT_L(0); PG8_MMA(1, 0, At, B0); PG8_BAR; PG8_SCHED;
;             PG8_STAGE(PG8_SB(1, 1), b3 + hstep, voffB);
;             PG8_WAIT_V(6); PG8_BAR; PG8_MMA(1, 1, At, B1); PG8_BAR;
	s_waitcnt lgkmcnt(0)
	s_waitcnt lgkmcnt(0)
	v_mfma_f32_16x16x32_bf16 v[60:63], v[128:131], v[144:147], v[60:63]
	v_mfma_f32_16x16x32_bf16 v[60:63], v[132:135], v[148:151], v[60:63]
	v_mfma_f32_16x16x32_bf16 v[56:59], v[140:143], v[148:151], v[56:59]
	v_mfma_f32_16x16x32_bf16 v[56:59], v[136:139], v[144:147], v[56:59]
	v_mfma_f32_16x16x32_bf16 v[40:43], v[136:139], v[152:155], v[40:43]
	v_mfma_f32_16x16x32_bf16 v[40:43], v[140:143], v[156:159], v[40:43]
	v_mfma_f32_16x16x32_bf16 v[44:47], v[132:135], v[156:159], v[44:47]
	v_mfma_f32_16x16x32_bf16 v[44:47], v[128:131], v[152:155], v[44:47]
	v_mfma_f32_16x16x32_bf16 v[28:31], v[128:131], v[160:163], v[28:31]
	v_mfma_f32_16x16x32_bf16 v[28:31], v[132:135], v[164:167], v[28:31]
	v_mfma_f32_16x16x32_bf16 v[24:27], v[140:143], v[164:167], v[24:27]
	v_mfma_f32_16x16x32_bf16 v[24:27], v[136:139], v[160:163], v[24:27]
	v_mfma_f32_16x16x32_bf16 v[8:11], v[136:139], v[168:171], v[8:11]
	v_mfma_f32_16x16x32_bf16 v[8:11], v[140:143], v[172:175], v[8:11]
	v_mfma_f32_16x16x32_bf16 v[12:15], v[132:135], v[172:175], v[12:15]
	v_mfma_f32_16x16x32_bf16 v[12:15], v[128:131], v[168:171], v[12:15]
	s_barrier
	s_add_u32 s42, s42, 0x40080
	s_addc_u32 s43, s43, 0
	s_add_i32 s44, s44, s51
	s_mov_b32 m0, s44
	s_nop 0
	global_load_lds_dwordx4 v178, s[42:43]
	s_add_i32 m0, s44, 0x2000
	s_nop 0
	global_load_lds_dwordx4 v182, s[42:43]
	s_waitcnt vmcnt(6)
	s_barrier
	v_mfma_f32_16x16x32_bf16 v[52:55], v[192:195], v[144:147], v[52:55]
	v_mfma_f32_16x16x32_bf16 v[52:55], v[196:199], v[148:151], v[52:55]
	v_mfma_f32_16x16x32_bf16 v[48:51], v[212:215], v[148:151], v[48:51]
	v_mfma_f32_16x16x32_bf16 v[48:51], v[200:203], v[144:147], v[48:51]
	v_mfma_f32_16x16x32_bf16 v[32:35], v[200:203], v[152:155], v[32:35]
	v_mfma_f32_16x16x32_bf16 v[32:35], v[212:215], v[156:159], v[32:35]
	v_mfma_f32_16x16x32_bf16 v[36:39], v[196:199], v[156:159], v[36:39]
	v_mfma_f32_16x16x32_bf16 v[36:39], v[192:195], v[152:155], v[36:39]
	v_mfma_f32_16x16x32_bf16 v[20:23], v[192:195], v[160:163], v[20:23]
	v_mfma_f32_16x16x32_bf16 v[20:23], v[196:199], v[164:167], v[20:23]
	v_mfma_f32_16x16x32_bf16 v[16:19], v[212:215], v[164:167], v[16:19]
	v_mfma_f32_16x16x32_bf16 v[16:19], v[200:203], v[160:163], v[16:19]
	v_mfma_f32_16x16x32_bf16 v[0:3], v[200:203], v[168:171], v[0:3]
	v_mfma_f32_16x16x32_bf16 v[0:3], v[212:215], v[172:175], v[0:3]
	v_mfma_f32_16x16x32_bf16 v[4:7], v[196:199], v[172:175], v[4:7]
	v_mfma_f32_16x16x32_bf16 v[4:7], v[192:195], v[168:171], v[4:7]
	s_add_i32 s41, s41, 2
	s_add_u32 s38, s38, 0x100
	s_addc_u32 s39, s39, 0
	s_add_u32 s21, s21, 0x100
	s_addc_u32 s23, s23, 0
	s_cmp_gt_u32 s41, 13
	s_barrier
	s_cbranch_scc0 .LBB0_353
; __device__ __forceinline__ unsigned cvt_pk_bf16(float lo, float hi) { unsigned r; asm volatile("v_cvt_pk_bf16_f32 %0, %1, %2" : "=v"(r) : "v"(lo), "v"(hi)); return r; }
; __device__ __forceinline__ float x16_sum(float x) { auto s = __builtin_amdgcn_permlane16_swap(__float_as_uint(x), __float_as_uint(x), false, false); return __uint_as_float(s[0]) + __uint_as_float(s[1]); }
; __device__ __forceinline__ float x32_sum(float x) { auto s = __builtin_amdgcn_permlane32_swap(__float_as_uint(x), __float_as_uint(x), false, false); return __uint_as_float(s[0]) + __uint_as_float(s[1]); }
;     __device__ __forceinline__ void operator()(const f32x4 (&acc)[2][2][4][2], const Unit& u, int ui, int wr, int wc, int fr, int fq) const {
;         const int row0 = u.pm * 256 + wr * 64 + fr, col0 = u.pn * 256 + wc * 32 + 8 * fq;
;         const float* xb0 = (u.pm * 256 < MP) ? xp : xs - (size_t)MP * DM;
; #pragma unroll
;         for (int ai = 0; ai < 2; ++ai) {
;             f32x4 xv[4][2][2];
; #pragma unroll
;             for (int m = 0; m < 4; ++m)
; #pragma unroll
;                 for (int bj = 0; bj < 2; ++bj) { const float* p = xb0 + (size_t)(row0 + ai * 128 + m * 16) * DM + col0 + bj * 128; xv[m][bj][0] = *(const f32x4*)p; xv[m][bj][1] = *(const f32x4*)(p + 4); }
; #pragma unroll
;             for (int m = 0; m < 4; ++m) { const int row = row0 + ai * 128 + m * 16; const size_t off = (size_t)row * DM + col0; float ss = 0.f;
; #pragma unroll
;                 for (int bj = 0; bj < 2; ++bj) {
;                     const f32x4 v0 = acc[ai][bj][m][0] + xv[m][bj][0], v1 = acc[ai][bj][m][1] + xv[m][bj][1];
;                     u32x4 w; w.x = cvt_pk_bf16(v0[0], v0[1]); w.y = cvt_pk_bf16(v0[2], v0[3]); w.z = cvt_pk_bf16(v1[0], v1[1]); w.w = cvt_pk_bf16(v1[2], v1[3]);
;                     *(u32x4*)(xb + off + bj * 128) = w;
;                     ss += (v0[0] * v0[0] + v0[1] * v0[1]) + (v0[2] * v0[2] + v0[3] * v0[3]) + (v1[0] * v1[0] + v1[1] * v1[1]) + (v1[2] * v1[2] + v1[3] * v1[3]); }
;                 ss = x32_sum(x16_sum(ss));
;                 if (fq == 0) part[(size_t)row * 16 + u.pn * 4 + wc] = ss; }
	s_nop 0
	s_nop 0
	s_nop 0
	s_nop 0
	s_nop 0
	s_nop 0
	s_nop 0
	s_nop 0
	s_nop 0
	s_nop 0
	s_nop 0
	s_nop 0
	s_nop 0
	s_nop 0
	s_nop 0
	s_nop 0
	s_nop 0
	s_nop 0
	s_nop 0
	s_nop 0
	s_nop 0
	s_nop 0
	s_nop 0
	s_nop 0
	s_nop 0
	s_nop 0
	s_nop 0
	s_nop 0
	s_nop 0
	s_nop 0
	s_nop 0
	s_nop 0
	s_cmpk_lt_i32 s40, 0x80
	v_lshl_add_u32 v194, s40, 8, v204
	v_lshl_or_b32 v192, s12, 8, v206
	s_cselect_b32 s21, s37, s61
	s_cselect_b32 s23, s36, s60
	v_mov_b32_e32 v128, s23
	v_mov_b32_e32 v129, s21
	v_ashrrev_i32_e32 v193, 31, v192
	v_ashrrev_i32_e32 v195, 31, v194
	v_lshl_add_u64 v[196:197], v[192:193], 2, v[128:129]
	v_lshlrev_b64 v[128:129], 12, v[194:195]
	v_or_b32_e32 v202, 16, v194
	v_or_b32_e32 v200, 32, v194
	v_or_b32_e32 v198, 48, v194
	v_lshl_add_u64 v[128:129], v[196:197], 0, v[128:129]
	v_ashrrev_i32_e32 v203, 31, v202
	v_ashrrev_i32_e32 v201, 31, v200
	v_ashrrev_i32_e32 v199, 31, v198
	global_load_dwordx4 v[212:215], v[128:129], off
	global_load_dwordx4 v[216:219], v[128:129], off offset:16
	global_load_dwordx4 v[220:223], v[128:129], off offset:512
	global_load_dwordx4 v[224:227], v[128:129], off offset:528
	v_lshlrev_b64 v[128:129], 12, v[202:203]
	v_lshlrev_b64 v[130:131], 12, v[200:201]
	v_lshlrev_b64 v[132:133], 12, v[198:199]
	v_lshl_add_u64 v[128:129], v[196:197], 0, v[128:129]
	v_lshl_add_u64 v[130:131], v[196:197], 0, v[130:131]
	v_lshl_add_u64 v[132:133], v[196:197], 0, v[132:133]
	global_load_dwordx4 v[168:171], v[128:129], off offset:16
	global_load_dwordx4 v[172:175], v[128:129], off
	global_load_dwordx4 v[160:163], v[128:129], off offset:528
	global_load_dwordx4 v[164:167], v[128:129], off offset:512
	global_load_dwordx4 v[152:155], v[130:131], off offset:16
	global_load_dwordx4 v[156:159], v[130:131], off
	global_load_dwordx4 v[144:147], v[130:131], off offset:528
	global_load_dwordx4 v[148:151], v[130:131], off offset:512
	global_load_dwordx4 v[136:139], v[132:133], off offset:16
	global_load_dwordx4 v[140:143], v[132:133], off
	s_nop 0
	global_load_dwordx4 v[128:131], v[132:133], off offset:528
	s_nop 0
	global_load_dwordx4 v[132:135], v[132:133], off offset:512
	v_lshlrev_b64 v[228:229], 11, v[194:195]
	v_lshl_add_u64 v[228:229], s[14:15], 0, v[228:229]
	v_lshl_add_u64 v[228:229], v[192:193], 1, v[228:229]
	s_lshl_b32 s38, s12, 2
	s_ashr_i32 s39, s38, 31
	s_waitcnt vmcnt(0)
	v_pk_add_f32 v[126:127], v[126:127], v[214:215]
	v_pk_add_f32 v[124:125], v[124:125], v[212:213]
	v_pk_add_f32 v[118:119], v[118:119], v[222:223]
	v_pk_add_f32 v[116:117], v[116:117], v[220:221]
	v_pk_add_f32 v[120:121], v[120:121], v[216:217]
	v_pk_add_f32 v[214:215], v[112:113], v[224:225]
	v_cvt_pk_bf16_f32 v112, v124, v125
	v_cvt_pk_bf16_f32 v113, v126, v127
	v_mul_f32_e32 v125, v125, v125
	v_mul_f32_e32 v127, v127, v127
	v_mul_f32_e32 v211, v117, v117
	v_mul_f32_e32 v216, v119, v119
	v_pk_add_f32 v[122:123], v[122:123], v[218:219]
	v_pk_add_f32 v[212:213], v[114:115], v[226:227]
	v_cvt_pk_bf16_f32 v114, v120, v121
	v_cvt_pk_bf16_f32 v115, v122, v123
	v_mul_f32_e32 v121, v121, v121
	v_mul_f32_e32 v217, v215, v215
	global_store_dwordx4 v[228:229], v[112:115], off
	v_fmac_f32_e32 v125, v124, v124
	v_fmac_f32_e32 v127, v126, v126
	v_cvt_pk_bf16_f32 v112, v116, v117
	v_fmac_f32_e32 v211, v116, v116
	v_fmac_f32_e32 v216, v118, v118
	v_mul_f32_e32 v123, v123, v123
	v_mul_f32_e32 v218, v213, v213
	v_fmac_f32_e32 v121, v120, v120
	v_cvt_pk_bf16_f32 v113, v118, v119
	v_cvt_pk_bf16_f32 v114, v214, v215
	v_cvt_pk_bf16_f32 v115, v212, v213
	v_fmac_f32_e32 v217, v214, v214
	v_add_f32_e32 v116, v125, v127
	global_store_dwordx4 v[228:229], v[112:115], off offset:256
	v_fmac_f32_e32 v123, v122, v122
	v_fmac_f32_e32 v218, v212, v212
	v_add_f32_e32 v112, v211, v216
	v_add_f32_e32 v113, v116, v121
	v_add_f32_e32 v112, v112, v217
	v_add_f32_e32 v113, v123, v113
	v_add_f32_e32 v112, v218, v112
	v_add_f32_e32 v112, v113, v112
	v_mov_b32_e32 v113, v112
	s_nop 1
	v_permlane16_swap_b32_e32 v112, v113
	v_add_f32_e32 v112, v112, v113
	v_mov_b32_e32 v113, v112
	s_nop 1
	v_permlane32_swap_b32_e32 v112, v113
	s_and_saveexec_b64 s[40:41], s[6:7]
	s_cbranch_execz .LBB0_356
	v_lshlrev_b64 v[114:115], 6, v[194:195]
	v_lshl_add_u64 v[114:115], s[16:17], 0, v[114:115]
	v_lshl_add_u64 v[114:115], s[38:39], 2, v[114:115]
	s_lshl_b32 s12, s62, 2
	v_lshl_add_u64 v[114:115], v[114:115], 0, s[12:13]
	v_add_f32_e32 v112, v112, v113
	global_store_dword v[114:115], v112, off

; #define PG8_STAGE(bufoff, gbase, voff) do { _Pragma("unroll") for (int _i = 0; _i < 2; ++_i) \
;         __builtin_amdgcn_global_load_lds((const unsigned*)((const char*)(gbase) + (voff)[_i]), (LAS unsigned*)(lds + (bufoff) + ldsw + _i * 8192), 16, 0, 0); } while (0)
; #define PG8_LDA(dst, b, h) do { _Pragma("unroll") for (int m = 0; m < 4; ++m) _Pragma("unroll") for (int k = 0; k < 2; ++k) dst[m][k] = *(const LAS bf16x8*)(lds + PG8_SA(b, h) + aoff + m * 2048 + k * 1024); } while (0)
; #define PG8_LDB(dst, b, h) do { _Pragma("unroll") for (int n = 0; n < 2; ++n) _Pragma("unroll") for (int k = 0; k < 2; ++k) dst[n][k] = *(const LAS bf16x8*)(lds + PG8_SB(b, h) + boff + n * 2048 + k * 1024); } while (0)
; #define PG8_MMA(ai, bj, At, Bt) do { __builtin_amdgcn_s_setprio(1); _Pragma("unroll") for (int m = 0; m < 4; ++m) _Pragma("unroll") for (int n = 0; n < 2; ++n) _Pragma("unroll") for (int k = 0; k < 2; ++k) \
;         acc[ai][bj][m][n] = __builtin_amdgcn_mfma_f32_16x16x32_bf16(Bt[n][k], At[m][k], acc[ai][bj][m][n], 0, 0, 0); __builtin_amdgcn_s_setprio(0); } while (0)
; #define PG8_WAIT_V(n) asm volatile("s_waitcnt vmcnt(" #n ")" ::: "memory")
; #define PG8_WAIT_L(n) asm volatile("s_waitcnt lgkmcnt(" #n ")" ::: "memory")
; #define PG8_BAR __builtin_amdgcn_s_barrier()
; template <class Epi, class Ptrs>
; __device__ __forceinline__ void gemm_phase(LAS unsigned char* lds, const int K, const StaticOrder& S, const Ptrs& P, const Epi& E) {
;     ...
;             const bool last = (t == nt - 2);
;             const char* a1 = cA + (size_t)(t + 1) * kstep;
;             const char* a2 = last ? nA : cA + (size_t)(t + 2) * kstep; const char* b2 = last ? nB : cB + (size_t)(t + 2) * kstep;
;             const char* a3 = a2 + kstep; const char* b3 = b2 + kstep;
;             PG8_LDB(B0, 0, 0); PG8_SCHED; PG8_LDA(At, 0, 0); PG8_STAGE(PG8_SA(1, 1), a1 + hstep, voffA);
;             PG8_WAIT_L(8); PG8_BAR; PG8_WAIT_L(0); PG8_MMA(0, 0, At, B0); PG8_BAR; PG8_SCHED;
;             PG8_LDB(B1, 0, 1); PG8_STAGE(PG8_SB(0, 0), b2, voffB);
;             PG8_BAR; PG8_WAIT_L(0); PG8_MMA(0, 1, At, B1); PG8_BAR;
;             PG8_LDA(At, 0, 1); PG8_STAGE(PG8_SA(0, 0), a2, voffA);
;             PG8_BAR; PG8_WAIT_L(0); PG8_MMA(1, 0, At, B0); PG8_BAR; PG8_SCHED;
;             PG8_STAGE(PG8_SB(0, 1), b2 + hstep, voffB);
;             PG8_WAIT_V(6); PG8_BAR; PG8_MMA(1, 1, At, B1); PG8_BAR;
.LBB0_433:
	ds_read_b128 v[152:155], v149
	ds_read_b128 v[156:159], v149 offset:1024
	ds_read_b128 v[160:163], v149 offset:2048
	ds_read_b128 v[164:167], v149 offset:3072
	s_add_u32 s42, s40, 0xfffc0080
	s_addc_u32 s43, s41, -1
	s_cmp_eq_u32 s70, 12
	s_cselect_b32 s45, s1, s43
	s_cselect_b32 s44, s0, s42
	s_cselect_b32 s43, s37, s25
	s_cselect_b32 s42, s36, s23
	s_add_i32 m0, s39, 0xc000
	ds_read_b128 v[168:171], v150
	ds_read_b128 v[172:175], v150 offset:1024
	ds_read_b128 v[176:179], v150 offset:2048
	ds_read_b128 v[180:183], v150 offset:3072
	ds_read_b128 v[184:187], v150 offset:4096
	ds_read_b128 v[188:191], v150 offset:5120
	ds_read_b128 v[192:195], v150 offset:6144
	ds_read_b128 v[196:199], v150 offset:7168
	global_load_lds_dwordx4 v136, s[40:41]
	s_add_i32 m0, s39, 0xe000
	s_nop 0
	global_load_lds_dwordx4 v138, s[40:41]
	s_waitcnt lgkmcnt(8)
	s_barrier
	s_waitcnt lgkmcnt(0)
	s_waitcnt lgkmcnt(0)
	v_mfma_f32_16x16x32_bf16 v[124:127], v[152:155], v[168:171], v[124:127]
	v_mfma_f32_16x16x32_bf16 v[124:127], v[156:159], v[172:175], v[124:127]
	v_mfma_f32_16x16x32_bf16 v[120:123], v[164:167], v[172:175], v[120:123]
	v_mfma_f32_16x16x32_bf16 v[120:123], v[160:163], v[168:171], v[120:123]
	v_mfma_f32_16x16x32_bf16 v[104:107], v[160:163], v[176:179], v[104:107]
	v_mfma_f32_16x16x32_bf16 v[104:107], v[164:167], v[180:183], v[104:107]
	v_mfma_f32_16x16x32_bf16 v[108:111], v[156:159], v[180:183], v[108:111]
	v_mfma_f32_16x16x32_bf16 v[108:111], v[152:155], v[176:179], v[108:111]
	v_mfma_f32_16x16x32_bf16 v[92:95], v[152:155], v[184:187], v[92:95]
	v_mfma_f32_16x16x32_bf16 v[92:95], v[156:159], v[188:191], v[92:95]
	v_mfma_f32_16x16x32_bf16 v[88:91], v[164:167], v[188:191], v[88:91]
	v_mfma_f32_16x16x32_bf16 v[88:91], v[160:163], v[184:187], v[88:91]
	v_mfma_f32_16x16x32_bf16 v[72:75], v[160:163], v[192:195], v[72:75]
	v_mfma_f32_16x16x32_bf16 v[72:75], v[164:167], v[196:199], v[72:75]
	v_mfma_f32_16x16x32_bf16 v[76:79], v[156:159], v[196:199], v[76:79]
	v_mfma_f32_16x16x32_bf16 v[76:79], v[152:155], v[192:195], v[76:79]
	s_barrier
	s_add_i32 s71, s63, s51
	v_lshl_add_u64 v[144:145], s[42:43], 0, v[130:131]
	s_mov_b32 m0, s71
	ds_read_b128 v[200:203], v151
	ds_read_b128 v[204:207], v151 offset:1024
	ds_read_b128 v[210:213], v151 offset:2048
	ds_read_b128 v[214:217], v151 offset:3072
	global_load_lds_dwordx4 v[144:145], off
	v_lshl_add_u64 v[218:219], s[42:43], 0, v[134:135]
	s_add_i32 m0, s71, 0x2000
	s_nop 0
	global_load_lds_dwordx4 v[218:219], off
	s_barrier
	s_waitcnt lgkmcnt(0)
	s_waitcnt lgkmcnt(0)
	v_mfma_f32_16x16x32_bf16 v[116:119], v[200:203], v[168:171], v[116:119]
	v_mfma_f32_16x16x32_bf16 v[116:119], v[204:207], v[172:175], v[116:119]
	v_mfma_f32_16x16x32_bf16 v[112:115], v[214:217], v[172:175], v[112:115]
	v_mfma_f32_16x16x32_bf16 v[112:115], v[210:213], v[168:171], v[112:115]
	v_mfma_f32_16x16x32_bf16 v[96:99], v[210:213], v[176:179], v[96:99]
	v_mfma_f32_16x16x32_bf16 v[96:99], v[214:217], v[180:183], v[96:99]
	v_mfma_f32_16x16x32_bf16 v[100:103], v[204:207], v[180:183], v[100:103]
	v_mfma_f32_16x16x32_bf16 v[100:103], v[200:203], v[176:179], v[100:103]
	v_mfma_f32_16x16x32_bf16 v[84:87], v[200:203], v[184:187], v[84:87]
	v_mfma_f32_16x16x32_bf16 v[84:87], v[204:207], v[188:191], v[84:87]
	v_mfma_f32_16x16x32_bf16 v[80:83], v[214:217], v[188:191], v[80:83]
	v_mfma_f32_16x16x32_bf16 v[80:83], v[210:213], v[184:187], v[80:83]
	v_mfma_f32_16x16x32_bf16 v[64:67], v[210:213], v[192:195], v[64:67]
	v_mfma_f32_16x16x32_bf16 v[64:67], v[214:217], v[196:199], v[64:67]
	v_mfma_f32_16x16x32_bf16 v[68:71], v[204:207], v[196:199], v[68:71]
	v_mfma_f32_16x16x32_bf16 v[68:71], v[200:203], v[192:195], v[68:71]
	s_mov_b32 m0, s39
	v_lshl_add_u64 v[220:221], s[44:45], 0, v[128:129]
	s_barrier
	ds_read_b128 v[168:171], v150 offset:16384
	ds_read_b128 v[172:175], v150 offset:17408
	ds_read_b128 v[176:179], v150 offset:18432
	ds_read_b128 v[180:183], v150 offset:19456
	ds_read_b128 v[184:187], v150 offset:20480
	ds_read_b128 v[188:191], v150 offset:21504
	ds_read_b128 v[192:195], v150 offset:22528
	ds_read_b128 v[196:199], v150 offset:23552
	global_load_lds_dwordx4 v[220:221], off
	v_lshl_add_u64 v[222:223], s[44:45], 0, v[132:133]
	s_mov_b32 m0, s56
	s_nop 0
	global_load_lds_dwordx4 v[222:223], off
	s_barrier
	s_waitcnt lgkmcnt(0)
	s_waitcnt lgkmcnt(0)
	v_mfma_f32_16x16x32_bf16 v[60:63], v[152:155], v[168:171], v[60:63]
	v_mfma_f32_16x16x32_bf16 v[60:63], v[156:159], v[172:175], v[60:63]
	v_mfma_f32_16x16x32_bf16 v[56:59], v[164:167], v[172:175], v[56:59]
	v_mfma_f32_16x16x32_bf16 v[56:59], v[160:163], v[168:171], v[56:59]
	v_mfma_f32_16x16x32_bf16 v[40:43], v[160:163], v[176:179], v[40:43]
	v_mfma_f32_16x16x32_bf16 v[40:43], v[164:167], v[180:183], v[40:43]
	v_mfma_f32_16x16x32_bf16 v[44:47], v[156:159], v[180:183], v[44:47]
	v_mfma_f32_16x16x32_bf16 v[44:47], v[152:155], v[176:179], v[44:47]
	v_mfma_f32_16x16x32_bf16 v[28:31], v[152:155], v[184:187], v[28:31]
	v_mfma_f32_16x16x32_bf16 v[28:31], v[156:159], v[188:191], v[28:31]
	v_mfma_f32_16x16x32_bf16 v[24:27], v[164:167], v[188:191], v[24:27]
	v_mfma_f32_16x16x32_bf16 v[24:27], v[160:163], v[184:187], v[24:27]
	v_mfma_f32_16x16x32_bf16 v[8:11], v[160:163], v[192:195], v[8:11]
	v_mfma_f32_16x16x32_bf16 v[8:11], v[164:167], v[196:199], v[8:11]
	v_mfma_f32_16x16x32_bf16 v[12:15], v[156:159], v[196:199], v[12:15]
	v_mfma_f32_16x16x32_bf16 v[12:15], v[152:155], v[192:195], v[12:15]
	s_barrier
	s_add_u32 s72, s42, 0x40000
	s_addc_u32 s73, s43, 0
	s_add_i32 s71, s64, s51
	s_mov_b32 m0, s71
	s_nop 0
	global_load_lds_dwordx4 v130, s[72:73]
	s_add_i32 m0, s71, 0x2000
	s_nop 0
	global_load_lds_dwordx4 v134, s[72:73]
	s_waitcnt vmcnt(6)
	s_barrier
; #define PG8_STAGE(bufoff, gbase, voff) do { _Pragma("unroll") for (int _i = 0; _i < 2; ++_i) \
;         __builtin_amdgcn_global_load_lds((const unsigned*)((const char*)(gbase) + (voff)[_i]), (LAS unsigned*)(lds + (bufoff) + ldsw + _i * 8192), 16, 0, 0); } while (0)
; #define PG8_LDA(dst, b, h) do { _Pragma("unroll") for (int m = 0; m < 4; ++m) _Pragma("unroll") for (int k = 0; k < 2; ++k) dst[m][k] = *(const LAS bf16x8*)(lds + PG8_SA(b, h) + aoff + m * 2048 + k * 1024); } while (0)
; #define PG8_LDB(dst, b, h) do { _Pragma("unroll") for (int n = 0; n < 2; ++n) _Pragma("unroll") for (int k = 0; k < 2; ++k) dst[n][k] = *(const LAS bf16x8*)(lds + PG8_SB(b, h) + boff + n * 2048 + k * 1024); } while (0)
; #define PG8_MMA(ai, bj, At, Bt) do { __builtin_amdgcn_s_setprio(1); _Pragma("unroll") for (int m = 0; m < 4; ++m) _Pragma("unroll") for (int n = 0; n < 2; ++n) _Pragma("unroll") for (int k = 0; k < 2; ++k) \
;         acc[ai][bj][m][n] = __builtin_amdgcn_mfma_f32_16x16x32_bf16(Bt[n][k], At[m][k], acc[ai][bj][m][n], 0, 0, 0); __builtin_amdgcn_s_setprio(0); } while (0)
; #define PG8_WAIT_V(n) asm volatile("s_waitcnt vmcnt(" #n ")" ::: "memory")
; #define PG8_WAIT_L(n) asm volatile("s_waitcnt lgkmcnt(" #n ")" ::: "memory")
; #define PG8_BAR __builtin_amdgcn_s_barrier()
; #define PG8_SCHED __builtin_amdgcn_sched_barrier(0)
; template <class Epi, class Ptrs>
; __device__ __forceinline__ void gemm_phase(LAS unsigned char* lds, const int K, const StaticOrder& S, const Ptrs& P, const Epi& E) {
;     ...
;             PG8_WAIT_V(6); PG8_BAR; PG8_MMA(1, 1, At, B1); PG8_BAR;
;             PG8_LDB(B0, 1, 0); PG8_SCHED; PG8_LDA(At, 1, 0); PG8_STAGE(PG8_SA(0, 1), a2 + hstep, voffA);
;             PG8_WAIT_L(8); PG8_BAR; PG8_WAIT_L(0); PG8_MMA(0, 0, At, B0); PG8_BAR; PG8_SCHED;
;             PG8_LDB(B1, 1, 1); PG8_STAGE(PG8_SB(1, 0), b3, voffB);
;             PG8_BAR; PG8_WAIT_L(0); PG8_MMA(0, 1, At, B1); PG8_BAR;
;             PG8_LDA(At, 1, 1); PG8_STAGE(PG8_SA(1, 0), a3, voffA);
	v_mfma_f32_16x16x32_bf16 v[52:55], v[200:203], v[168:171], v[52:55]
	v_mfma_f32_16x16x32_bf16 v[52:55], v[204:207], v[172:175], v[52:55]
	v_mfma_f32_16x16x32_bf16 v[48:51], v[214:217], v[172:175], v[48:51]
	v_mfma_f32_16x16x32_bf16 v[48:51], v[210:213], v[168:171], v[48:51]
	v_mfma_f32_16x16x32_bf16 v[32:35], v[210:213], v[176:179], v[32:35]
	v_mfma_f32_16x16x32_bf16 v[32:35], v[214:217], v[180:183], v[32:35]
	v_mfma_f32_16x16x32_bf16 v[36:39], v[204:207], v[180:183], v[36:39]
	v_mfma_f32_16x16x32_bf16 v[36:39], v[200:203], v[176:179], v[36:39]
	v_mfma_f32_16x16x32_bf16 v[20:23], v[200:203], v[184:187], v[20:23]
	v_mfma_f32_16x16x32_bf16 v[20:23], v[204:207], v[188:191], v[20:23]
	v_mfma_f32_16x16x32_bf16 v[16:19], v[214:217], v[188:191], v[16:19]
	v_mfma_f32_16x16x32_bf16 v[16:19], v[210:213], v[184:187], v[16:19]
	v_mfma_f32_16x16x32_bf16 v[0:3], v[210:213], v[192:195], v[0:3]
	v_mfma_f32_16x16x32_bf16 v[0:3], v[214:217], v[196:199], v[0:3]
	v_mfma_f32_16x16x32_bf16 v[4:7], v[204:207], v[196:199], v[4:7]
	v_mfma_f32_16x16x32_bf16 v[4:7], v[200:203], v[192:195], v[4:7]
	s_add_i32 s71, 0, 0x18000
	v_add_u32_e32 v164, s71, v147
	s_barrier
	ds_read_b128 v[152:155], v164
	ds_read_b128 v[156:159], v164 offset:1024
	ds_read_b128 v[160:163], v164 offset:2048
	ds_read_b128 v[164:167], v164 offset:3072
	s_add_u32 s44, s44, 0x40000
	s_addc_u32 s45, s45, 0
	s_mov_b32 m0, s57
	ds_read_b128 v[168:171], v150 offset:32768
	ds_read_b128 v[172:175], v150 offset:33792
	ds_read_b128 v[176:179], v150 offset:34816
	ds_read_b128 v[180:183], v150 offset:35840
	ds_read_b128 v[184:187], v150 offset:36864
	ds_read_b128 v[188:191], v150 offset:37888
	ds_read_b128 v[192:195], v150 offset:38912
	ds_read_b128 v[196:199], v150 offset:39936
	global_load_lds_dwordx4 v128, s[44:45]
	s_mov_b32 m0, s58
	s_nop 0
	global_load_lds_dwordx4 v132, s[44:45]
	s_waitcnt lgkmcnt(8)
	s_barrier
	s_waitcnt lgkmcnt(0)
	s_waitcnt lgkmcnt(0)
	v_mfma_f32_16x16x32_bf16 v[124:127], v[152:155], v[168:171], v[124:127]
	v_mfma_f32_16x16x32_bf16 v[124:127], v[156:159], v[172:175], v[124:127]
	v_mfma_f32_16x16x32_bf16 v[120:123], v[164:167], v[172:175], v[120:123]
	v_mfma_f32_16x16x32_bf16 v[120:123], v[160:163], v[168:171], v[120:123]
	v_mfma_f32_16x16x32_bf16 v[104:107], v[160:163], v[176:179], v[104:107]
	v_mfma_f32_16x16x32_bf16 v[104:107], v[164:167], v[180:183], v[104:107]
	v_mfma_f32_16x16x32_bf16 v[108:111], v[156:159], v[180:183], v[108:111]
	v_mfma_f32_16x16x32_bf16 v[108:111], v[152:155], v[176:179], v[108:111]
	v_mfma_f32_16x16x32_bf16 v[92:95], v[152:155], v[184:187], v[92:95]
	v_mfma_f32_16x16x32_bf16 v[92:95], v[156:159], v[188:191], v[92:95]
	v_mfma_f32_16x16x32_bf16 v[88:91], v[164:167], v[188:191], v[88:91]
	v_mfma_f32_16x16x32_bf16 v[88:91], v[160:163], v[184:187], v[88:91]
	v_mfma_f32_16x16x32_bf16 v[72:75], v[160:163], v[192:195], v[72:75]
	v_mfma_f32_16x16x32_bf16 v[72:75], v[164:167], v[196:199], v[72:75]
	v_mfma_f32_16x16x32_bf16 v[76:79], v[156:159], v[196:199], v[76:79]
	v_mfma_f32_16x16x32_bf16 v[76:79], v[152:155], v[192:195], v[76:79]
	s_barrier
	s_add_i32 s44, 0, 0x1c000
	s_add_i32 s45, s71, s51
	v_add_u32_e32 v209, s44, v147
	v_lshl_add_u64 v[144:145], v[144:145], 0, s[12:13]
	s_mov_b32 m0, s45
	ds_read_b128 v[200:203], v209
	ds_read_b128 v[204:207], v209 offset:1024
	ds_read_b128 v[210:213], v209 offset:2048
	ds_read_b128 v[214:217], v209 offset:3072
	global_load_lds_dwordx4 v[144:145], off
	v_lshl_add_u64 v[144:145], v[218:219], 0, s[12:13]
	s_add_i32 m0, s45, 0x2000
	s_nop 0
	global_load_lds_dwordx4 v[144:145], off
	s_barrier
	s_waitcnt lgkmcnt(0)
	s_waitcnt lgkmcnt(0)
	v_mfma_f32_16x16x32_bf16 v[116:119], v[200:203], v[168:171], v[116:119]
	v_mfma_f32_16x16x32_bf16 v[116:119], v[204:207], v[172:175], v[116:119]
	v_mfma_f32_16x16x32_bf16 v[112:115], v[214:217], v[172:175], v[112:115]
	v_mfma_f32_16x16x32_bf16 v[112:115], v[210:213], v[168:171], v[112:115]
	v_mfma_f32_16x16x32_bf16 v[96:99], v[210:213], v[176:179], v[96:99]
	v_mfma_f32_16x16x32_bf16 v[96:99], v[214:217], v[180:183], v[96:99]
	v_mfma_f32_16x16x32_bf16 v[100:103], v[204:207], v[180:183], v[100:103]
	v_mfma_f32_16x16x32_bf16 v[100:103], v[200:203], v[176:179], v[100:103]
	v_mfma_f32_16x16x32_bf16 v[84:87], v[200:203], v[184:187], v[84:87]
	v_mfma_f32_16x16x32_bf16 v[84:87], v[204:207], v[188:191], v[84:87]
	v_mfma_f32_16x16x32_bf16 v[80:83], v[214:217], v[188:191], v[80:83]
	v_mfma_f32_16x16x32_bf16 v[80:83], v[210:213], v[184:187], v[80:83]
	v_mfma_f32_16x16x32_bf16 v[64:67], v[210:213], v[192:195], v[64:67]
	v_mfma_f32_16x16x32_bf16 v[64:67], v[214:217], v[196:199], v[64:67]
	v_mfma_f32_16x16x32_bf16 v[68:71], v[204:207], v[196:199], v[68:71]
	v_mfma_f32_16x16x32_bf16 v[68:71], v[200:203], v[192:195], v[68:71]
	s_mov_b32 m0, s61
	v_lshl_add_u64 v[144:145], v[220:221], 0, s[12:13]
	s_barrier
	ds_read_b128 v[168:171], v150 offset:49152
	ds_read_b128 v[172:175], v150 offset:50176
	ds_read_b128 v[176:179], v150 offset:51200
	ds_read_b128 v[180:183], v150 offset:52224
	ds_read_b128 v[184:187], v150 offset:53248
	ds_read_b128 v[188:191], v150 offset:54272
	ds_read_b128 v[192:195], v150 offset:55296
	ds_read_b128 v[196:199], v150 offset:56320
	global_load_lds_dwordx4 v[144:145], off
	v_lshl_add_u64 v[144:145], v[222:223], 0, s[12:13]
	s_mov_b32 m0, s62
	s_nop 0
	global_load_lds_dwordx4 v[144:145], off
	s_barrier
; __device__ __forceinline__ unsigned cvt_pk_bf16(float lo, float hi) { unsigned r; asm volatile("v_cvt_pk_bf16_f32 %0, %1, %2" : "=v"(r) : "v"(lo), "v"(hi)); return r; }
; #define PG8_STAGE(bufoff, gbase, voff) do { _Pragma("unroll") for (int _i = 0; _i < 2; ++_i) \
;         __builtin_amdgcn_global_load_lds((const unsigned*)((const char*)(gbase) + (voff)[_i]), (LAS unsigned*)(lds + (bufoff) + ldsw + _i * 8192), 16, 0, 0); } while (0)
; #define PG8_MMA(ai, bj, At, Bt) do { __builtin_amdgcn_s_setprio(1); _Pragma("unroll") for (int m = 0; m < 4; ++m) _Pragma("unroll") for (int n = 0; n < 2; ++n) _Pragma("unroll") for (int k = 0; k < 2; ++k) \
;         acc[ai][bj][m][n] = __builtin_amdgcn_mfma_f32_16x16x32_bf16(Bt[n][k], At[m][k], acc[ai][bj][m][n], 0, 0, 0); __builtin_amdgcn_s_setprio(0); } while (0)
; #define PG8_WAIT_V(n) asm volatile("s_waitcnt vmcnt(" #n ")" ::: "memory")
; #define PG8_WAIT_L(n) asm volatile("s_waitcnt lgkmcnt(" #n ")" ::: "memory")
; #define PG8_BAR __builtin_amdgcn_s_barrier()
; #define PG8_SCHED __builtin_amdgcn_sched_barrier(0)
; template <class Epi, class Ptrs>
; __device__ __forceinline__ void gemm_phase(LAS unsigned char* lds, const int K, const StaticOrder& S, const Ptrs& P, const Epi& E) {
;     ...
;             PG8_BAR; PG8_WAIT_L(0); PG8_MMA(1, 0, At, B0); PG8_BAR; PG8_SCHED;
;             PG8_STAGE(PG8_SB(1, 1), b3 + hstep, voffB);
;             PG8_WAIT_V(6); PG8_BAR; PG8_MMA(1, 1, At, B1); PG8_BAR;
;     __device__ __forceinline__ void operator()(const f32x4 (&acc)[2][2][4][2], const Unit& u, int ui, int wr, int wc, int fr, int fq) const {
;         const int row0 = u.pm * 256 + wr * 64 + fr, col0 = u.pn * 256 + wc * 32 + 8 * fq;
; #pragma unroll
;         for (int ai = 0; ai < 2; ++ai)
; #pragma unroll
;             for (int m = 0; m < 4; ++m) { bf16_t* rowp = hid + (size_t)(row0 + ai * 128 + m * 16) * DFF + col0;
; #pragma unroll
;                 for (int bj = 0; bj < 2; ++bj) { f32x4 v0 = acc[ai][bj][m][0], v1 = acc[ai][bj][m][1];
; #pragma unroll
;                     for (int j = 0; j < 4; ++j) { const float a = fmaxf(v0[j], 0.f), b = fmaxf(v1[j], 0.f); v0[j] = a * a; v1[j] = b * b; }
;                     u32x4 w; w.x = cvt_pk_bf16(v0[0], v0[1]); w.y = cvt_pk_bf16(v0[2], v0[3]); w.z = cvt_pk_bf16(v1[0], v1[1]); w.w = cvt_pk_bf16(v1[2], v1[3]);
;                     *(u32x4*)(rowp + bj * 128) = w; } }
	s_waitcnt lgkmcnt(0)
	s_waitcnt lgkmcnt(0)
	v_mfma_f32_16x16x32_bf16 v[60:63], v[152:155], v[168:171], v[60:63]
	v_mfma_f32_16x16x32_bf16 v[60:63], v[156:159], v[172:175], v[60:63]
	v_mfma_f32_16x16x32_bf16 v[56:59], v[164:167], v[172:175], v[56:59]
	v_mfma_f32_16x16x32_bf16 v[56:59], v[160:163], v[168:171], v[56:59]
	v_mfma_f32_16x16x32_bf16 v[40:43], v[160:163], v[176:179], v[40:43]
	v_mfma_f32_16x16x32_bf16 v[40:43], v[164:167], v[180:183], v[40:43]
	v_mfma_f32_16x16x32_bf16 v[44:47], v[156:159], v[180:183], v[44:47]
	v_mfma_f32_16x16x32_bf16 v[44:47], v[152:155], v[176:179], v[44:47]
	v_mfma_f32_16x16x32_bf16 v[28:31], v[152:155], v[184:187], v[28:31]
	v_mfma_f32_16x16x32_bf16 v[28:31], v[156:159], v[188:191], v[28:31]
	v_mfma_f32_16x16x32_bf16 v[24:27], v[164:167], v[188:191], v[24:27]
	v_mfma_f32_16x16x32_bf16 v[24:27], v[160:163], v[184:187], v[24:27]
	v_mfma_f32_16x16x32_bf16 v[8:11], v[160:163], v[192:195], v[8:11]
	v_mfma_f32_16x16x32_bf16 v[8:11], v[164:167], v[196:199], v[8:11]
	v_mfma_f32_16x16x32_bf16 v[12:15], v[156:159], v[196:199], v[12:15]
	v_mfma_f32_16x16x32_bf16 v[12:15], v[152:155], v[192:195], v[12:15]
	s_barrier
	s_add_u32 s42, s42, 0x40080
	s_addc_u32 s43, s43, 0
	s_add_i32 s44, s44, s51
	s_mov_b32 m0, s44
	s_nop 0
	global_load_lds_dwordx4 v130, s[42:43]
	s_add_i32 m0, s44, 0x2000
	s_nop 0
	global_load_lds_dwordx4 v134, s[42:43]
	s_waitcnt vmcnt(6)
	s_barrier
	v_mfma_f32_16x16x32_bf16 v[52:55], v[200:203], v[168:171], v[52:55]
	v_mfma_f32_16x16x32_bf16 v[52:55], v[204:207], v[172:175], v[52:55]
	v_mfma_f32_16x16x32_bf16 v[48:51], v[214:217], v[172:175], v[48:51]
	v_mfma_f32_16x16x32_bf16 v[48:51], v[210:213], v[168:171], v[48:51]
	v_mfma_f32_16x16x32_bf16 v[32:35], v[210:213], v[176:179], v[32:35]
	v_mfma_f32_16x16x32_bf16 v[32:35], v[214:217], v[180:183], v[32:35]
	v_mfma_f32_16x16x32_bf16 v[36:39], v[204:207], v[180:183], v[36:39]
	v_mfma_f32_16x16x32_bf16 v[36:39], v[200:203], v[176:179], v[36:39]
	v_mfma_f32_16x16x32_bf16 v[20:23], v[200:203], v[184:187], v[20:23]
	v_mfma_f32_16x16x32_bf16 v[20:23], v[204:207], v[188:191], v[20:23]
	v_mfma_f32_16x16x32_bf16 v[16:19], v[214:217], v[188:191], v[16:19]
	v_mfma_f32_16x16x32_bf16 v[16:19], v[210:213], v[184:187], v[16:19]
	v_mfma_f32_16x16x32_bf16 v[0:3], v[210:213], v[192:195], v[0:3]
	v_mfma_f32_16x16x32_bf16 v[0:3], v[214:217], v[196:199], v[0:3]
	v_mfma_f32_16x16x32_bf16 v[4:7], v[204:207], v[196:199], v[4:7]
	v_mfma_f32_16x16x32_bf16 v[4:7], v[200:203], v[192:195], v[4:7]
	s_add_i32 s70, s70, 2
	s_add_u32 s40, s40, 0x100
	s_addc_u32 s41, s41, 0
	s_add_u32 s23, s23, 0x100
	s_addc_u32 s25, s25, 0
	s_cmp_gt_u32 s70, 13
	s_barrier
	s_cbranch_scc0 .LBB0_433
	s_nop 0
	s_nop 0
	s_nop 0
	s_nop 0
	s_nop 0
	s_nop 0
	s_nop 0
	s_nop 0
	s_nop 0
	s_nop 0
	s_nop 0
	s_nop 0
	s_nop 0
	s_nop 0
	s_nop 0
	s_nop 0
	s_nop 0
	s_nop 0
	s_nop 0
	s_nop 0
	s_nop 0
	s_nop 0
	s_nop 0
	s_nop 0
	s_nop 0
	s_nop 0
	s_nop 0
	s_nop 0
	s_nop 0
	s_nop 0
	s_nop 0
	s_nop 0
	v_lshl_add_u32 v152, s38, 8, v146
	v_max_f32_e32 v120, 0, v120
	v_ashrrev_i32_e32 v153, 31, v152
	v_max_f32_e32 v121, 0, v121
	v_max_f32_e32 v122, 0, v122
	v_lshl_or_b32 v144, s69, 8, v148
	v_lshlrev_b64 v[154:155], 13, v[152:153]
	v_mul_f32_e32 v153, v120, v120
	v_max_f32_e32 v120, 0, v125
	v_ashrrev_i32_e32 v145, 31, v144
	v_max_f32_e32 v124, 0, v124
	v_mul_f32_e32 v125, v121, v121
	v_max_f32_e32 v121, 0, v126
	v_mul_f32_e32 v126, v122, v122
	v_max_f32_e32 v122, 0, v127
	v_max_f32_e32 v123, 0, v123
	v_lshl_add_u64 v[154:155], s[10:11], 0, v[154:155]
	v_lshlrev_b64 v[156:157], 1, v[144:145]
	v_mul_f32_e32 v120, v120, v120
	v_max_f32_e32 v112, 0, v112
	v_lshl_add_u64 v[144:145], v[154:155], 0, v[156:157]
	v_mul_f32_e32 v124, v124, v124
	v_mul_f32_e32 v121, v121, v121
	v_mul_f32_e32 v122, v122, v122
	v_mul_f32_e32 v123, v123, v123
	v_cvt_pk_bf16_f32 v120, v124, v120
	v_max_f32_e32 v113, 0, v113
	v_max_f32_e32 v114, 0, v114
	v_cvt_pk_bf16_f32 v121, v121, v122
	v_cvt_pk_bf16_f32 v122, v153, v125
	v_cvt_pk_bf16_f32 v123, v126, v123
	global_store_dwordx4 v[144:145], v[120:123], off
	s_nop 1
	v_mul_f32_e32 v120, v112, v112
	v_max_f32_e32 v112, 0, v117
	v_max_f32_e32 v116, 0, v116
	v_mul_f32_e32 v117, v113, v113
	v_max_f32_e32 v113, 0, v118
	v_mul_f32_e32 v118, v114, v114
	v_max_f32_e32 v114, 0, v119
	v_max_f32_e32 v115, 0, v115
	v_mul_f32_e32 v112, v112, v112
	v_mul_f32_e32 v116, v116, v116
	v_mul_f32_e32 v113, v113, v113
	v_mul_f32_e32 v114, v114, v114
	v_mul_f32_e32 v115, v115, v115
	v_cvt_pk_bf16_f32 v112, v116, v112
	v_max_f32_e32 v104, 0, v104
	v_cvt_pk_bf16_f32 v113, v113, v114
	v_cvt_pk_bf16_f32 v114, v120, v117
	v_cvt_pk_bf16_f32 v115, v118, v115
	global_store_dwordx4 v[144:145], v[112:115], off offset:256
	s_nop 0
	v_max_f32_e32 v105, 0, v105
	v_or_b32_e32 v112, 16, v152
	v_max_f32_e32 v106, 0, v106
	v_ashrrev_i32_e32 v113, 31, v112
	v_mul_f32_e32 v114, v104, v104
	v_max_f32_e32 v104, 0, v109
	v_lshlrev_b64 v[112:113], 13, v[112:113]
	v_max_f32_e32 v108, 0, v108
	v_mul_f32_e32 v109, v105, v105
	v_max_f32_e32 v105, 0, v110
	v_mul_f32_e32 v110, v106, v106
	v_max_f32_e32 v106, 0, v111
	v_max_f32_e32 v107, 0, v107
	v_lshl_add_u64 v[112:113], s[10:11], 0, v[112:113]
	v_mul_f32_e32 v104, v104, v104
	v_max_f32_e32 v96, 0, v96
	v_lshl_add_u64 v[112:113], v[112:113], 0, v[156:157]
	v_mul_f32_e32 v108, v108, v108
	v_mul_f32_e32 v105, v105, v105
	v_mul_f32_e32 v106, v106, v106
	v_mul_f32_e32 v107, v107, v107
	v_cvt_pk_bf16_f32 v104, v108, v104
	v_max_f32_e32 v97, 0, v97
	v_max_f32_e32 v98, 0, v98
	v_cvt_pk_bf16_f32 v105, v105, v106
	v_cvt_pk_bf16_f32 v106, v114, v109
	v_cvt_pk_bf16_f32 v107, v110, v107
	global_store_dwordx4 v[112:113], v[104:107], off
; __device__ __forceinline__ unsigned cvt_pk_bf16(float lo, float hi) { unsigned r; asm volatile("v_cvt_pk_bf16_f32 %0, %1, %2" : "=v"(r) : "v"(lo), "v"(hi)); return r; }
;     __device__ __forceinline__ void operator()(const f32x4 (&acc)[2][2][4][2], const Unit& u, int ui, int wr, int wc, int fr, int fq) const {
;         const int row0 = u.pm * 256 + wr * 64 + fr, col0 = u.pn * 256 + wc * 32 + 8 * fq;
; #pragma unroll
;         for (int ai = 0; ai < 2; ++ai)
; #pragma unroll
;             for (int m = 0; m < 4; ++m) { bf16_t* rowp = hid + (size_t)(row0 + ai * 128 + m * 16) * DFF + col0;
; #pragma unroll
;                 for (int bj = 0; bj < 2; ++bj) { f32x4 v0 = acc[ai][bj][m][0], v1 = acc[ai][bj][m][1];
; #pragma unroll
;                     for (int j = 0; j < 4; ++j) { const float a = fmaxf(v0[j], 0.f), b = fmaxf(v1[j], 0.f); v0[j] = a * a; v1[j] = b * b; }
;                     u32x4 w; w.x = cvt_pk_bf16(v0[0], v0[1]); w.y = cvt_pk_bf16(v0[2], v0[3]); w.z = cvt_pk_bf16(v1[0], v1[1]); w.w = cvt_pk_bf16(v1[2], v1[3]);
;                     *(u32x4*)(rowp + bj * 128) = w; } }
	s_nop 1
	v_mul_f32_e32 v104, v96, v96
	v_max_f32_e32 v96, 0, v101
	v_max_f32_e32 v100, 0, v100
	v_mul_f32_e32 v101, v97, v97
	v_max_f32_e32 v97, 0, v102
	v_mul_f32_e32 v102, v98, v98
	v_max_f32_e32 v98, 0, v103
	v_max_f32_e32 v99, 0, v99
	v_mul_f32_e32 v96, v96, v96
	v_mul_f32_e32 v100, v100, v100
	v_mul_f32_e32 v97, v97, v97
	v_mul_f32_e32 v98, v98, v98
	v_mul_f32_e32 v99, v99, v99
	v_cvt_pk_bf16_f32 v96, v100, v96
	v_max_f32_e32 v88, 0, v88
	v_cvt_pk_bf16_f32 v97, v97, v98
	v_cvt_pk_bf16_f32 v98, v104, v101
	v_cvt_pk_bf16_f32 v99, v102, v99
	global_store_dwordx4 v[112:113], v[96:99], off offset:256
	s_nop 0
	v_max_f32_e32 v89, 0, v89
	v_or_b32_e32 v96, 32, v152
	v_max_f32_e32 v90, 0, v90
	v_ashrrev_i32_e32 v97, 31, v96
	v_mul_f32_e32 v98, v88, v88
	v_max_f32_e32 v88, 0, v93
	v_lshlrev_b64 v[96:97], 13, v[96:97]
	v_max_f32_e32 v92, 0, v92
	v_mul_f32_e32 v93, v89, v89
	v_max_f32_e32 v89, 0, v94
	v_mul_f32_e32 v94, v90, v90
	v_max_f32_e32 v90, 0, v95
	v_max_f32_e32 v91, 0, v91
	v_lshl_add_u64 v[96:97], s[10:11], 0, v[96:97]
	v_mul_f32_e32 v88, v88, v88
	v_max_f32_e32 v80, 0, v80
	v_lshl_add_u64 v[96:97], v[96:97], 0, v[156:157]
	v_mul_f32_e32 v92, v92, v92
	v_mul_f32_e32 v89, v89, v89
	v_mul_f32_e32 v90, v90, v90
	v_mul_f32_e32 v91, v91, v91
	v_cvt_pk_bf16_f32 v88, v92, v88
	v_max_f32_e32 v81, 0, v81
	v_max_f32_e32 v82, 0, v82
	v_cvt_pk_bf16_f32 v89, v89, v90
	v_cvt_pk_bf16_f32 v90, v98, v93
	v_cvt_pk_bf16_f32 v91, v94, v91
	global_store_dwordx4 v[96:97], v[88:91], off
	s_nop 1
	v_mul_f32_e32 v88, v80, v80
	v_max_f32_e32 v80, 0, v85
	v_max_f32_e32 v84, 0, v84
	v_mul_f32_e32 v85, v81, v81
	v_max_f32_e32 v81, 0, v86
	v_mul_f32_e32 v86, v82, v82
	v_max_f32_e32 v82, 0, v87
	v_max_f32_e32 v83, 0, v83
	v_mul_f32_e32 v80, v80, v80
	v_mul_f32_e32 v84, v84, v84
	v_mul_f32_e32 v81, v81, v81
	v_mul_f32_e32 v82, v82, v82
	v_mul_f32_e32 v83, v83, v83
	v_cvt_pk_bf16_f32 v80, v84, v80
	v_max_f32_e32 v72, 0, v72
	v_cvt_pk_bf16_f32 v81, v81, v82
	v_cvt_pk_bf16_f32 v82, v88, v85
	v_cvt_pk_bf16_f32 v83, v86, v83
	global_store_dwordx4 v[96:97], v[80:83], off offset:256
	s_nop 0
	v_max_f32_e32 v73, 0, v73
	v_or_b32_e32 v80, 48, v152
	v_max_f32_e32 v74, 0, v74
	v_ashrrev_i32_e32 v81, 31, v80
	v_mul_f32_e32 v82, v72, v72
	v_max_f32_e32 v72, 0, v77
	v_lshlrev_b64 v[80:81], 13, v[80:81]
	v_max_f32_e32 v76, 0, v76
	v_mul_f32_e32 v77, v73, v73
	v_max_f32_e32 v73, 0, v78
	v_mul_f32_e32 v78, v74, v74
	v_max_f32_e32 v74, 0, v79
	v_max_f32_e32 v75, 0, v75
	v_lshl_add_u64 v[80:81], s[10:11], 0, v[80:81]
	v_mul_f32_e32 v72, v72, v72
	v_max_f32_e32 v64, 0, v64
	v_max_f32_e32 v65, 0, v65
	v_max_f32_e32 v66, 0, v66
	v_lshl_add_u64 v[80:81], v[80:81], 0, v[156:157]
	v_mul_f32_e32 v76, v76, v76
	v_mul_f32_e32 v73, v73, v73
	v_mul_f32_e32 v74, v74, v74
	v_mul_f32_e32 v75, v75, v75
	v_cvt_pk_bf16_f32 v72, v76, v72
	v_cvt_pk_bf16_f32 v73, v73, v74
	v_cvt_pk_bf16_f32 v74, v82, v77
	v_cvt_pk_bf16_f32 v75, v78, v75
	global_store_dwordx4 v[80:81], v[72:75], off
	v_max_f32_e32 v68, 0, v68
	v_max_f32_e32 v67, 0, v67
	v_mul_f32_e32 v72, v64, v64
	v_max_f32_e32 v64, 0, v69
	v_mul_f32_e32 v69, v65, v65
	v_max_f32_e32 v65, 0, v70
	v_mul_f32_e32 v70, v66, v66
	v_max_f32_e32 v66, 0, v71
	v_mul_f32_e32 v64, v64, v64
	v_mul_f32_e32 v65, v65, v65
	v_mul_f32_e32 v66, v66, v66
	v_max_f32_e32 v56, 0, v56
	v_mul_f32_e32 v68, v68, v68
	v_mul_f32_e32 v67, v67, v67
	v_cvt_pk_bf16_f32 v64, v68, v64
	v_cvt_pk_bf16_f32 v65, v65, v66
	v_cvt_pk_bf16_f32 v66, v72, v69
	v_max_f32_e32 v57, 0, v57
	v_max_f32_e32 v58, 0, v58
	v_cvt_pk_bf16_f32 v67, v70, v67
	global_store_dwordx4 v[80:81], v[64:67], off offset:256
	s_nop 0
	v_max_f32_e32 v60, 0, v60
	v_mul_f32_e32 v66, v56, v56
	v_max_f32_e32 v56, 0, v61
	v_mul_f32_e32 v61, v57, v57
	v_max_f32_e32 v57, 0, v62
	v_mul_f32_e32 v62, v58, v58
	v_max_f32_e32 v58, 0, v63
	v_mul_f32_e32 v60, v60, v60
	v_mul_f32_e32 v56, v56, v56
	v_max_f32_e32 v59, 0, v59
	v_mul_f32_e32 v57, v57, v57
	v_mul_f32_e32 v58, v58, v58
	v_cvt_pk_bf16_f32 v56, v60, v56
	v_add_co_u32_e32 v60, vcc, s65, v144
	v_max_f32_e32 v48, 0, v48
	v_max_f32_e32 v49, 0, v49
	v_max_f32_e32 v50, 0, v50
	v_mul_f32_e32 v59, v59, v59
	v_cvt_pk_bf16_f32 v57, v57, v58
	v_cvt_pk_bf16_f32 v58, v66, v61
	v_addc_co_u32_e32 v61, vcc, 0, v145, vcc
	v_cvt_pk_bf16_f32 v59, v62, v59
	global_store_dwordx4 v[60:61], v[56:59], off
	v_max_f32_e32 v52, 0, v52
	v_max_f32_e32 v51, 0, v51
	v_mul_f32_e32 v56, v48, v48
	v_max_f32_e32 v48, 0, v53
	v_mul_f32_e32 v53, v49, v49
	v_max_f32_e32 v49, 0, v54
	v_mul_f32_e32 v54, v50, v50
	v_max_f32_e32 v50, 0, v55
	v_mul_f32_e32 v48, v48, v48
	v_mul_f32_e32 v49, v49, v49
	v_mul_f32_e32 v50, v50, v50
	v_max_f32_e32 v40, 0, v40
; __device__ __forceinline__ unsigned cvt_pk_bf16(float lo, float hi) { unsigned r; asm volatile("v_cvt_pk_bf16_f32 %0, %1, %2" : "=v"(r) : "v"(lo), "v"(hi)); return r; }
; #define PG8_WAIT_V(n) asm volatile("s_waitcnt vmcnt(" #n ")" ::: "memory")
; #define PG8_BAR __builtin_amdgcn_s_barrier()
; template <class Epi, class Ptrs>
; __device__ __forceinline__ void gemm_phase(LAS unsigned char* lds, const int K, const StaticOrder& S, const Ptrs& P, const Epi& E) {
;     ...
;     PG8_WAIT_V(0);
;     if (wr == 0) PG8_BAR;
;     __device__ __forceinline__ void operator()(const f32x4 (&acc)[2][2][4][2], const Unit& u, int ui, int wr, int wc, int fr, int fq) const {
;         const int row0 = u.pm * 256 + wr * 64 + fr, col0 = u.pn * 256 + wc * 32 + 8 * fq;
; #pragma unroll
;         for (int ai = 0; ai < 2; ++ai)
; #pragma unroll
;             for (int m = 0; m < 4; ++m) { bf16_t* rowp = hid + (size_t)(row0 + ai * 128 + m * 16) * DFF + col0;
; #pragma unroll
;                 for (int bj = 0; bj < 2; ++bj) { f32x4 v0 = acc[ai][bj][m][0], v1 = acc[ai][bj][m][1];
; #pragma unroll
;                     for (int j = 0; j < 4; ++j) { const float a = fmaxf(v0[j], 0.f), b = fmaxf(v1[j], 0.f); v0[j] = a * a; v1[j] = b * b; }
;                     u32x4 w; w.x = cvt_pk_bf16(v0[0], v0[1]); w.y = cvt_pk_bf16(v0[2], v0[3]); w.z = cvt_pk_bf16(v1[0], v1[1]); w.w = cvt_pk_bf16(v1[2], v1[3]);
;                     *(u32x4*)(rowp + bj * 128) = w; } }
	v_lshl_add_u64 v[64:65], v[144:145], 0, s[14:15]
	v_mul_f32_e32 v52, v52, v52
	v_mul_f32_e32 v51, v51, v51
	v_cvt_pk_bf16_f32 v48, v52, v48
	v_cvt_pk_bf16_f32 v49, v49, v50
	v_cvt_pk_bf16_f32 v50, v56, v53
	v_max_f32_e32 v41, 0, v41
	v_max_f32_e32 v42, 0, v42
	v_cvt_pk_bf16_f32 v51, v54, v51
	global_store_dwordx4 v[64:65], v[48:51], off offset:256
	s_nop 0
	v_max_f32_e32 v44, 0, v44
	v_mul_f32_e32 v50, v40, v40
	v_max_f32_e32 v40, 0, v45
	v_mul_f32_e32 v45, v41, v41
	v_max_f32_e32 v41, 0, v46
	v_mul_f32_e32 v46, v42, v42
	v_max_f32_e32 v42, 0, v47
	v_mul_f32_e32 v44, v44, v44
	v_mul_f32_e32 v40, v40, v40
	v_max_f32_e32 v43, 0, v43
	v_mul_f32_e32 v41, v41, v41
	v_mul_f32_e32 v42, v42, v42
	v_cvt_pk_bf16_f32 v40, v44, v40
	v_add_co_u32_e32 v44, vcc, s66, v144
	v_max_f32_e32 v32, 0, v32
	v_max_f32_e32 v33, 0, v33
	v_max_f32_e32 v34, 0, v34
	v_mul_f32_e32 v43, v43, v43
	v_cvt_pk_bf16_f32 v41, v41, v42
	v_cvt_pk_bf16_f32 v42, v50, v45
	v_addc_co_u32_e32 v45, vcc, 0, v145, vcc
	v_cvt_pk_bf16_f32 v43, v46, v43
	global_store_dwordx4 v[44:45], v[40:43], off
	v_max_f32_e32 v36, 0, v36
	v_max_f32_e32 v35, 0, v35
	v_mul_f32_e32 v40, v32, v32
	v_max_f32_e32 v32, 0, v37
	v_mul_f32_e32 v37, v33, v33
	v_max_f32_e32 v33, 0, v38
	v_mul_f32_e32 v38, v34, v34
	v_max_f32_e32 v34, 0, v39
	v_mul_f32_e32 v32, v32, v32
	v_mul_f32_e32 v33, v33, v33
	v_mul_f32_e32 v34, v34, v34
	v_max_f32_e32 v24, 0, v24
	v_lshl_add_u64 v[48:49], v[144:145], 0, s[16:17]
	v_mul_f32_e32 v36, v36, v36
	v_mul_f32_e32 v35, v35, v35
	v_cvt_pk_bf16_f32 v32, v36, v32
	v_cvt_pk_bf16_f32 v33, v33, v34
	v_cvt_pk_bf16_f32 v34, v40, v37
	v_max_f32_e32 v25, 0, v25
	v_max_f32_e32 v26, 0, v26
	v_cvt_pk_bf16_f32 v35, v38, v35
	global_store_dwordx4 v[48:49], v[32:35], off offset:256
	s_nop 0
	v_max_f32_e32 v28, 0, v28
	v_mul_f32_e32 v34, v24, v24
	v_max_f32_e32 v24, 0, v29
	v_mul_f32_e32 v29, v25, v25
	v_max_f32_e32 v25, 0, v30
	v_mul_f32_e32 v30, v26, v26
	v_max_f32_e32 v26, 0, v31
	v_mul_f32_e32 v28, v28, v28
	v_mul_f32_e32 v24, v24, v24
	v_max_f32_e32 v27, 0, v27
	v_mul_f32_e32 v25, v25, v25
	v_mul_f32_e32 v26, v26, v26
	v_cvt_pk_bf16_f32 v24, v28, v24
	v_add_co_u32_e32 v28, vcc, s67, v144
	v_max_f32_e32 v16, 0, v16
	v_max_f32_e32 v17, 0, v17
	v_max_f32_e32 v18, 0, v18
	v_mul_f32_e32 v27, v27, v27
	v_cvt_pk_bf16_f32 v25, v25, v26
	v_cvt_pk_bf16_f32 v26, v34, v29
	v_addc_co_u32_e32 v29, vcc, 0, v145, vcc
	v_cvt_pk_bf16_f32 v27, v30, v27
	global_store_dwordx4 v[28:29], v[24:27], off
	v_max_f32_e32 v20, 0, v20
	v_max_f32_e32 v19, 0, v19
	v_mul_f32_e32 v24, v16, v16
	v_max_f32_e32 v16, 0, v21
	v_mul_f32_e32 v21, v17, v17
	v_max_f32_e32 v17, 0, v22
	v_mul_f32_e32 v22, v18, v18
	v_max_f32_e32 v18, 0, v23
	v_mul_f32_e32 v16, v16, v16
	v_mul_f32_e32 v17, v17, v17
	v_mul_f32_e32 v18, v18, v18
	v_max_f32_e32 v8, 0, v8
	v_lshl_add_u64 v[32:33], v[144:145], 0, s[18:19]
	v_mul_f32_e32 v20, v20, v20
	v_mul_f32_e32 v19, v19, v19
	v_cvt_pk_bf16_f32 v16, v20, v16
	v_cvt_pk_bf16_f32 v17, v17, v18
	v_cvt_pk_bf16_f32 v18, v24, v21
	v_max_f32_e32 v9, 0, v9
	v_max_f32_e32 v10, 0, v10
	v_cvt_pk_bf16_f32 v19, v22, v19
	global_store_dwordx4 v[32:33], v[16:19], off offset:256
	s_nop 0
	v_max_f32_e32 v12, 0, v12
	v_mul_f32_e32 v18, v8, v8
	v_max_f32_e32 v8, 0, v13
	v_mul_f32_e32 v13, v9, v9
	v_max_f32_e32 v9, 0, v14
	v_mul_f32_e32 v14, v10, v10
	v_max_f32_e32 v10, 0, v15
	v_mul_f32_e32 v12, v12, v12
	v_mul_f32_e32 v8, v8, v8
	v_max_f32_e32 v11, 0, v11
	v_mul_f32_e32 v9, v9, v9
	v_mul_f32_e32 v10, v10, v10
	v_cvt_pk_bf16_f32 v8, v12, v8
	v_add_co_u32_e32 v12, vcc, s68, v144
	v_max_f32_e32 v0, 0, v0
	v_max_f32_e32 v1, 0, v1
	v_max_f32_e32 v2, 0, v2
	v_mul_f32_e32 v11, v11, v11
	v_cvt_pk_bf16_f32 v9, v9, v10
	v_cvt_pk_bf16_f32 v10, v18, v13
	v_addc_co_u32_e32 v13, vcc, 0, v145, vcc
	v_cvt_pk_bf16_f32 v11, v14, v11
	global_store_dwordx4 v[12:13], v[8:11], off
	v_max_f32_e32 v3, 0, v3
	v_max_f32_e32 v4, 0, v4
	v_mul_f32_e32 v8, v0, v0
	v_max_f32_e32 v0, 0, v5
	v_mul_f32_e32 v5, v1, v1
	v_max_f32_e32 v1, 0, v6
	v_mul_f32_e32 v6, v2, v2
	v_max_f32_e32 v2, 0, v7
	v_lshl_add_u64 v[16:17], v[144:145], 0, s[20:21]
	v_mul_f32_e32 v0, v0, v0
	v_mul_f32_e32 v1, v1, v1
	v_mul_f32_e32 v2, v2, v2
	v_mul_f32_e32 v3, v3, v3
	s_and_b64 vcc, exec, s[4:5]
	s_mov_b32 s69, s22
	s_mov_b32 s38, s24
	s_mov_b64 s[40:41], s[0:1]
	s_mov_b64 s[42:43], s[36:37]
	v_mul_f32_e32 v4, v4, v4
	v_cvt_pk_bf16_f32 v0, v4, v0
	v_cvt_pk_bf16_f32 v1, v1, v2
	v_cvt_pk_bf16_f32 v2, v8, v5
	v_cvt_pk_bf16_f32 v3, v6, v3
	global_store_dwordx4 v[16:17], v[0:3], off offset:256
	s_cbranch_vccz .LBB0_428
	s_waitcnt vmcnt(0)
	s_cmpk_gt_u32 s46, 0xff
	s_cbranch_scc1 .LBB0_437
	s_barrier

; #define PG8_STAGE(bufoff, gbase, voff) do { _Pragma("unroll") for (int _i = 0; _i < 2; ++_i) \
;         __builtin_amdgcn_global_load_lds((const unsigned*)((const char*)(gbase) + (voff)[_i]), (LAS unsigned*)(lds + (bufoff) + ldsw + _i * 8192), 16, 0, 0); } while (0)
; #define PG8_LDA(dst, b, h) do { _Pragma("unroll") for (int m = 0; m < 4; ++m) _Pragma("unroll") for (int k = 0; k < 2; ++k) dst[m][k] = *(const LAS bf16x8*)(lds + PG8_SA(b, h) + aoff + m * 2048 + k * 1024); } while (0)
; #define PG8_LDB(dst, b, h) do { _Pragma("unroll") for (int n = 0; n < 2; ++n) _Pragma("unroll") for (int k = 0; k < 2; ++k) dst[n][k] = *(const LAS bf16x8*)(lds + PG8_SB(b, h) + boff + n * 2048 + k * 1024); } while (0)
; #define PG8_MMA(ai, bj, At, Bt) do { __builtin_amdgcn_s_setprio(1); _Pragma("unroll") for (int m = 0; m < 4; ++m) _Pragma("unroll") for (int n = 0; n < 2; ++n) _Pragma("unroll") for (int k = 0; k < 2; ++k) \
;         acc[ai][bj][m][n] = __builtin_amdgcn_mfma_f32_16x16x32_bf16(Bt[n][k], At[m][k], acc[ai][bj][m][n], 0, 0, 0); __builtin_amdgcn_s_setprio(0); } while (0)
; #define PG8_WAIT_V(n) asm volatile("s_waitcnt vmcnt(" #n ")" ::: "memory")
; #define PG8_WAIT_L(n) asm volatile("s_waitcnt lgkmcnt(" #n ")" ::: "memory")
; #define PG8_BAR __builtin_amdgcn_s_barrier()
; template <class Epi, class Ptrs>
; __device__ __forceinline__ void gemm_phase(LAS unsigned char* lds, const int K, const StaticOrder& S, const Ptrs& P, const Epi& E) {
;     ...
;             const bool last = (t == nt - 2);
;             const char* a1 = cA + (size_t)(t + 1) * kstep;
;             const char* a2 = last ? nA : cA + (size_t)(t + 2) * kstep; const char* b2 = last ? nB : cB + (size_t)(t + 2) * kstep;
;             const char* a3 = a2 + kstep; const char* b3 = b2 + kstep;
;             PG8_LDB(B0, 0, 0); PG8_SCHED; PG8_LDA(At, 0, 0); PG8_STAGE(PG8_SA(1, 1), a1 + hstep, voffA);
;             PG8_WAIT_L(8); PG8_BAR; PG8_WAIT_L(0); PG8_MMA(0, 0, At, B0); PG8_BAR; PG8_SCHED;
;             PG8_LDB(B1, 0, 1); PG8_STAGE(PG8_SB(0, 0), b2, voffB);
;             PG8_BAR; PG8_WAIT_L(0); PG8_MMA(0, 1, At, B1); PG8_BAR;
;             PG8_LDA(At, 0, 1); PG8_STAGE(PG8_SA(0, 0), a2, voffA);
;             PG8_BAR; PG8_WAIT_L(0); PG8_MMA(1, 0, At, B0); PG8_BAR; PG8_SCHED;
;             PG8_STAGE(PG8_SB(0, 1), b2 + hstep, voffB);
;             PG8_WAIT_V(6); PG8_BAR; PG8_MMA(1, 1, At, B1); PG8_BAR;
.LBB0_522:
	ds_read_b128 v[128:131], v193
	ds_read_b128 v[132:135], v193 offset:1024
	ds_read_b128 v[136:139], v193 offset:2048
	ds_read_b128 v[140:143], v193 offset:3072
	s_add_u32 s22, s20, 0xfff00080
	s_addc_u32 s23, s21, -1
	s_cmp_eq_u32 s46, 60
	s_cselect_b32 s25, s5, s23
	s_cselect_b32 s24, s4, s22
	s_cselect_b32 s23, s15, s13
	s_cselect_b32 s22, s14, s11
	s_add_i32 m0, s17, 0xc000
	ds_read_b128 v[144:147], v194
	ds_read_b128 v[148:151], v194 offset:1024
	ds_read_b128 v[152:155], v194 offset:2048
	ds_read_b128 v[156:159], v194 offset:3072
	ds_read_b128 v[176:179], v194 offset:4096
	ds_read_b128 v[180:183], v194 offset:5120
	ds_read_b128 v[196:199], v194 offset:6144
	ds_read_b128 v[200:203], v194 offset:7168
	global_load_lds_dwordx4 v168, s[20:21]
	s_add_i32 m0, s17, 0xe000
	s_nop 0
	global_load_lds_dwordx4 v170, s[20:21]
	s_waitcnt lgkmcnt(8)
	s_barrier
	s_waitcnt lgkmcnt(0)
	s_waitcnt lgkmcnt(0)
	v_mfma_f32_16x16x32_bf16 v[124:127], v[128:131], v[144:147], v[124:127]
	v_mfma_f32_16x16x32_bf16 v[124:127], v[132:135], v[148:151], v[124:127]
	v_mfma_f32_16x16x32_bf16 v[120:123], v[140:143], v[148:151], v[120:123]
	v_mfma_f32_16x16x32_bf16 v[120:123], v[136:139], v[144:147], v[120:123]
	v_mfma_f32_16x16x32_bf16 v[104:107], v[136:139], v[152:155], v[104:107]
	v_mfma_f32_16x16x32_bf16 v[104:107], v[140:143], v[156:159], v[104:107]
	v_mfma_f32_16x16x32_bf16 v[112:115], v[132:135], v[156:159], v[112:115]
	v_mfma_f32_16x16x32_bf16 v[112:115], v[128:131], v[152:155], v[112:115]
	v_mfma_f32_16x16x32_bf16 v[92:95], v[128:131], v[176:179], v[92:95]
	v_mfma_f32_16x16x32_bf16 v[92:95], v[132:135], v[180:183], v[92:95]
	v_mfma_f32_16x16x32_bf16 v[88:91], v[140:143], v[180:183], v[88:91]
	v_mfma_f32_16x16x32_bf16 v[88:91], v[136:139], v[176:179], v[88:91]
	v_mfma_f32_16x16x32_bf16 v[72:75], v[136:139], v[196:199], v[72:75]
	v_mfma_f32_16x16x32_bf16 v[72:75], v[140:143], v[200:203], v[72:75]
	v_mfma_f32_16x16x32_bf16 v[76:79], v[132:135], v[200:203], v[76:79]
	v_mfma_f32_16x16x32_bf16 v[76:79], v[128:131], v[196:199], v[76:79]
	s_barrier
	s_add_i32 s47, s42, s34
	v_lshl_add_u64 v[184:185], s[22:23], 0, v[162:163]
	s_mov_b32 m0, s47
	ds_read_b128 v[204:207], v195
	ds_read_b128 v[208:211], v195 offset:1024
	ds_read_b128 v[212:215], v195 offset:2048
	ds_read_b128 v[216:219], v195 offset:3072
	global_load_lds_dwordx4 v[184:185], off
	v_lshl_add_u64 v[220:221], s[22:23], 0, v[166:167]
	s_add_i32 m0, s47, 0x2000
	s_nop 0
	global_load_lds_dwordx4 v[220:221], off
	s_barrier
	s_waitcnt lgkmcnt(0)
	s_waitcnt lgkmcnt(0)
	v_mfma_f32_16x16x32_bf16 v[116:119], v[204:207], v[144:147], v[116:119]
	v_mfma_f32_16x16x32_bf16 v[116:119], v[208:211], v[148:151], v[116:119]
	v_mfma_f32_16x16x32_bf16 v[108:111], v[216:219], v[148:151], v[108:111]
	v_mfma_f32_16x16x32_bf16 v[108:111], v[212:215], v[144:147], v[108:111]
	v_mfma_f32_16x16x32_bf16 v[96:99], v[212:215], v[152:155], v[96:99]
	v_mfma_f32_16x16x32_bf16 v[96:99], v[216:219], v[156:159], v[96:99]
	v_mfma_f32_16x16x32_bf16 v[100:103], v[208:211], v[156:159], v[100:103]
	v_mfma_f32_16x16x32_bf16 v[100:103], v[204:207], v[152:155], v[100:103]
	v_mfma_f32_16x16x32_bf16 v[84:87], v[204:207], v[176:179], v[84:87]
	v_mfma_f32_16x16x32_bf16 v[84:87], v[208:211], v[180:183], v[84:87]
	v_mfma_f32_16x16x32_bf16 v[80:83], v[216:219], v[180:183], v[80:83]
	v_mfma_f32_16x16x32_bf16 v[80:83], v[212:215], v[176:179], v[80:83]
	v_mfma_f32_16x16x32_bf16 v[64:67], v[212:215], v[196:199], v[64:67]
	v_mfma_f32_16x16x32_bf16 v[64:67], v[216:219], v[200:203], v[64:67]
	v_mfma_f32_16x16x32_bf16 v[68:71], v[208:211], v[200:203], v[68:71]
	v_mfma_f32_16x16x32_bf16 v[68:71], v[204:207], v[196:199], v[68:71]
	s_mov_b32 m0, s17
	v_lshl_add_u64 v[222:223], s[24:25], 0, v[160:161]
	s_barrier
	ds_read_b128 v[144:147], v194 offset:16384
	ds_read_b128 v[148:151], v194 offset:17408
	ds_read_b128 v[152:155], v194 offset:18432
	ds_read_b128 v[156:159], v194 offset:19456
	ds_read_b128 v[176:179], v194 offset:20480
	ds_read_b128 v[180:183], v194 offset:21504
	ds_read_b128 v[196:199], v194 offset:22528
	ds_read_b128 v[200:203], v194 offset:23552
	global_load_lds_dwordx4 v[222:223], off
	v_lshl_add_u64 v[224:225], s[24:25], 0, v[164:165]
	s_mov_b32 m0, s19
	s_nop 0
	global_load_lds_dwordx4 v[224:225], off
	s_barrier
	s_waitcnt lgkmcnt(0)
	s_waitcnt lgkmcnt(0)
	v_mfma_f32_16x16x32_bf16 v[60:63], v[128:131], v[144:147], v[60:63]
	v_mfma_f32_16x16x32_bf16 v[60:63], v[132:135], v[148:151], v[60:63]
	v_mfma_f32_16x16x32_bf16 v[56:59], v[140:143], v[148:151], v[56:59]
	v_mfma_f32_16x16x32_bf16 v[56:59], v[136:139], v[144:147], v[56:59]
	v_mfma_f32_16x16x32_bf16 v[40:43], v[136:139], v[152:155], v[40:43]
	v_mfma_f32_16x16x32_bf16 v[40:43], v[140:143], v[156:159], v[40:43]
	v_mfma_f32_16x16x32_bf16 v[48:51], v[132:135], v[156:159], v[48:51]
	v_mfma_f32_16x16x32_bf16 v[48:51], v[128:131], v[152:155], v[48:51]
	v_mfma_f32_16x16x32_bf16 v[32:35], v[128:131], v[176:179], v[32:35]
	v_mfma_f32_16x16x32_bf16 v[32:35], v[132:135], v[180:183], v[32:35]
	v_mfma_f32_16x16x32_bf16 v[24:27], v[140:143], v[180:183], v[24:27]
	v_mfma_f32_16x16x32_bf16 v[24:27], v[136:139], v[176:179], v[24:27]
	v_mfma_f32_16x16x32_bf16 v[8:11], v[136:139], v[196:199], v[8:11]
	v_mfma_f32_16x16x32_bf16 v[8:11], v[140:143], v[200:203], v[8:11]
	v_mfma_f32_16x16x32_bf16 v[16:19], v[132:135], v[200:203], v[16:19]
	v_mfma_f32_16x16x32_bf16 v[16:19], v[128:131], v[196:199], v[16:19]
	s_barrier
	s_add_u32 s48, s22, 0x100000
	s_addc_u32 s49, s23, 0
	s_add_i32 s47, s43, s34
	s_mov_b32 m0, s47
	s_nop 0
	global_load_lds_dwordx4 v162, s[48:49]
	s_add_i32 m0, s47, 0x2000
	s_nop 0
	global_load_lds_dwordx4 v166, s[48:49]
	s_waitcnt vmcnt(6)
	s_barrier
; #define PG8_STAGE(bufoff, gbase, voff) do { _Pragma("unroll") for (int _i = 0; _i < 2; ++_i) \
;         __builtin_amdgcn_global_load_lds((const unsigned*)((const char*)(gbase) + (voff)[_i]), (LAS unsigned*)(lds + (bufoff) + ldsw + _i * 8192), 16, 0, 0); } while (0)
; #define PG8_LDA(dst, b, h) do { _Pragma("unroll") for (int m = 0; m < 4; ++m) _Pragma("unroll") for (int k = 0; k < 2; ++k) dst[m][k] = *(const LAS bf16x8*)(lds + PG8_SA(b, h) + aoff + m * 2048 + k * 1024); } while (0)
; #define PG8_LDB(dst, b, h) do { _Pragma("unroll") for (int n = 0; n < 2; ++n) _Pragma("unroll") for (int k = 0; k < 2; ++k) dst[n][k] = *(const LAS bf16x8*)(lds + PG8_SB(b, h) + boff + n * 2048 + k * 1024); } while (0)
; #define PG8_MMA(ai, bj, At, Bt) do { __builtin_amdgcn_s_setprio(1); _Pragma("unroll") for (int m = 0; m < 4; ++m) _Pragma("unroll") for (int n = 0; n < 2; ++n) _Pragma("unroll") for (int k = 0; k < 2; ++k) \
;         acc[ai][bj][m][n] = __builtin_amdgcn_mfma_f32_16x16x32_bf16(Bt[n][k], At[m][k], acc[ai][bj][m][n], 0, 0, 0); __builtin_amdgcn_s_setprio(0); } while (0)
; #define PG8_WAIT_V(n) asm volatile("s_waitcnt vmcnt(" #n ")" ::: "memory")
; #define PG8_WAIT_L(n) asm volatile("s_waitcnt lgkmcnt(" #n ")" ::: "memory")
; #define PG8_BAR __builtin_amdgcn_s_barrier()
; #define PG8_SCHED __builtin_amdgcn_sched_barrier(0)
; template <class Epi, class Ptrs>
; __device__ __forceinline__ void gemm_phase(LAS unsigned char* lds, const int K, const StaticOrder& S, const Ptrs& P, const Epi& E) {
;     ...
;             PG8_WAIT_V(6); PG8_BAR; PG8_MMA(1, 1, At, B1); PG8_BAR;
;             PG8_LDB(B0, 1, 0); PG8_SCHED; PG8_LDA(At, 1, 0); PG8_STAGE(PG8_SA(0, 1), a2 + hstep, voffA);
;             PG8_WAIT_L(8); PG8_BAR; PG8_WAIT_L(0); PG8_MMA(0, 0, At, B0); PG8_BAR; PG8_SCHED;
;             PG8_LDB(B1, 1, 1); PG8_STAGE(PG8_SB(1, 0), b3, voffB);
;             PG8_BAR; PG8_WAIT_L(0); PG8_MMA(0, 1, At, B1); PG8_BAR;
;             PG8_LDA(At, 1, 1); PG8_STAGE(PG8_SA(1, 0), a3, voffA);
	v_mfma_f32_16x16x32_bf16 v[52:55], v[204:207], v[144:147], v[52:55]
	v_mfma_f32_16x16x32_bf16 v[52:55], v[208:211], v[148:151], v[52:55]
	v_mfma_f32_16x16x32_bf16 v[44:47], v[216:219], v[148:151], v[44:47]
	v_mfma_f32_16x16x32_bf16 v[44:47], v[212:215], v[144:147], v[44:47]
	v_mfma_f32_16x16x32_bf16 v[28:31], v[212:215], v[152:155], v[28:31]
	v_mfma_f32_16x16x32_bf16 v[28:31], v[216:219], v[156:159], v[28:31]
	v_mfma_f32_16x16x32_bf16 v[36:39], v[208:211], v[156:159], v[36:39]
	v_mfma_f32_16x16x32_bf16 v[36:39], v[204:207], v[152:155], v[36:39]
	v_mfma_f32_16x16x32_bf16 v[20:23], v[204:207], v[176:179], v[20:23]
	v_mfma_f32_16x16x32_bf16 v[20:23], v[208:211], v[180:183], v[20:23]
	v_mfma_f32_16x16x32_bf16 v[12:15], v[216:219], v[180:183], v[12:15]
	v_mfma_f32_16x16x32_bf16 v[12:15], v[212:215], v[176:179], v[12:15]
	v_mfma_f32_16x16x32_bf16 v[0:3], v[212:215], v[196:199], v[0:3]
	v_mfma_f32_16x16x32_bf16 v[0:3], v[216:219], v[200:203], v[0:3]
	v_mfma_f32_16x16x32_bf16 v[4:7], v[208:211], v[200:203], v[4:7]
	v_mfma_f32_16x16x32_bf16 v[4:7], v[204:207], v[196:199], v[4:7]
	s_add_i32 s47, 0, 0x18000
	v_add_u32_e32 v140, s47, v187
	s_barrier
	ds_read_b128 v[128:131], v140
	ds_read_b128 v[132:135], v140 offset:1024
	ds_read_b128 v[136:139], v140 offset:2048
	ds_read_b128 v[140:143], v140 offset:3072
	s_add_u32 s24, s24, 0x100000
	s_addc_u32 s25, s25, 0
	s_mov_b32 m0, s40
	ds_read_b128 v[144:147], v194 offset:32768
	ds_read_b128 v[148:151], v194 offset:33792
	ds_read_b128 v[152:155], v194 offset:34816
	ds_read_b128 v[156:159], v194 offset:35840
	ds_read_b128 v[176:179], v194 offset:36864
	ds_read_b128 v[180:183], v194 offset:37888
	ds_read_b128 v[196:199], v194 offset:38912
	ds_read_b128 v[200:203], v194 offset:39936
	global_load_lds_dwordx4 v160, s[24:25]
	s_mov_b32 m0, s41
	s_nop 0
	global_load_lds_dwordx4 v164, s[24:25]
	s_waitcnt lgkmcnt(8)
	s_barrier
	s_waitcnt lgkmcnt(0)
	s_waitcnt lgkmcnt(0)
	v_mfma_f32_16x16x32_bf16 v[124:127], v[128:131], v[144:147], v[124:127]
	v_mfma_f32_16x16x32_bf16 v[124:127], v[132:135], v[148:151], v[124:127]
	v_mfma_f32_16x16x32_bf16 v[120:123], v[140:143], v[148:151], v[120:123]
	v_mfma_f32_16x16x32_bf16 v[120:123], v[136:139], v[144:147], v[120:123]
	v_mfma_f32_16x16x32_bf16 v[104:107], v[136:139], v[152:155], v[104:107]
	v_mfma_f32_16x16x32_bf16 v[104:107], v[140:143], v[156:159], v[104:107]
	v_mfma_f32_16x16x32_bf16 v[112:115], v[132:135], v[156:159], v[112:115]
	v_mfma_f32_16x16x32_bf16 v[112:115], v[128:131], v[152:155], v[112:115]
	v_mfma_f32_16x16x32_bf16 v[92:95], v[128:131], v[176:179], v[92:95]
	v_mfma_f32_16x16x32_bf16 v[92:95], v[132:135], v[180:183], v[92:95]
	v_mfma_f32_16x16x32_bf16 v[88:91], v[140:143], v[180:183], v[88:91]
	v_mfma_f32_16x16x32_bf16 v[88:91], v[136:139], v[176:179], v[88:91]
	v_mfma_f32_16x16x32_bf16 v[72:75], v[136:139], v[196:199], v[72:75]
	v_mfma_f32_16x16x32_bf16 v[72:75], v[140:143], v[200:203], v[72:75]
	v_mfma_f32_16x16x32_bf16 v[76:79], v[132:135], v[200:203], v[76:79]
	v_mfma_f32_16x16x32_bf16 v[76:79], v[128:131], v[196:199], v[76:79]
	s_barrier
	s_add_i32 s24, 0, 0x1c000
	s_add_i32 s25, s47, s34
	v_add_u32_e32 v216, s24, v187
	v_lshl_add_u64 v[184:185], v[184:185], 0, s[8:9]
	s_mov_b32 m0, s25
	ds_read_b128 v[204:207], v216
	ds_read_b128 v[208:211], v216 offset:1024
	ds_read_b128 v[212:215], v216 offset:2048
	ds_read_b128 v[216:219], v216 offset:3072
	global_load_lds_dwordx4 v[184:185], off
	v_lshl_add_u64 v[184:185], v[220:221], 0, s[8:9]
	s_add_i32 m0, s25, 0x2000
	s_nop 0
	global_load_lds_dwordx4 v[184:185], off
	s_barrier
	s_waitcnt lgkmcnt(0)
	s_waitcnt lgkmcnt(0)
	v_mfma_f32_16x16x32_bf16 v[116:119], v[204:207], v[144:147], v[116:119]
	v_mfma_f32_16x16x32_bf16 v[116:119], v[208:211], v[148:151], v[116:119]
	v_mfma_f32_16x16x32_bf16 v[108:111], v[216:219], v[148:151], v[108:111]
	v_mfma_f32_16x16x32_bf16 v[108:111], v[212:215], v[144:147], v[108:111]
	v_mfma_f32_16x16x32_bf16 v[96:99], v[212:215], v[152:155], v[96:99]
	v_mfma_f32_16x16x32_bf16 v[96:99], v[216:219], v[156:159], v[96:99]
	v_mfma_f32_16x16x32_bf16 v[100:103], v[208:211], v[156:159], v[100:103]
	v_mfma_f32_16x16x32_bf16 v[100:103], v[204:207], v[152:155], v[100:103]
	v_mfma_f32_16x16x32_bf16 v[84:87], v[204:207], v[176:179], v[84:87]
	v_mfma_f32_16x16x32_bf16 v[84:87], v[208:211], v[180:183], v[84:87]
	v_mfma_f32_16x16x32_bf16 v[80:83], v[216:219], v[180:183], v[80:83]
	v_mfma_f32_16x16x32_bf16 v[80:83], v[212:215], v[176:179], v[80:83]
	v_mfma_f32_16x16x32_bf16 v[64:67], v[212:215], v[196:199], v[64:67]
	v_mfma_f32_16x16x32_bf16 v[64:67], v[216:219], v[200:203], v[64:67]
	v_mfma_f32_16x16x32_bf16 v[68:71], v[208:211], v[200:203], v[68:71]
	v_mfma_f32_16x16x32_bf16 v[68:71], v[204:207], v[196:199], v[68:71]
	s_mov_b32 m0, s28
	v_lshl_add_u64 v[184:185], v[222:223], 0, s[8:9]
	s_barrier
	ds_read_b128 v[144:147], v194 offset:49152
	ds_read_b128 v[148:151], v194 offset:50176
	ds_read_b128 v[152:155], v194 offset:51200
	ds_read_b128 v[156:159], v194 offset:52224
	ds_read_b128 v[176:179], v194 offset:53248
	ds_read_b128 v[180:183], v194 offset:54272
	ds_read_b128 v[196:199], v194 offset:55296
	ds_read_b128 v[200:203], v194 offset:56320
	global_load_lds_dwordx4 v[184:185], off
	v_lshl_add_u64 v[184:185], v[224:225], 0, s[8:9]
	s_mov_b32 m0, s29
	s_nop 0
	global_load_lds_dwordx4 v[184:185], off
	s_barrier
; __device__ __forceinline__ float bf_lo(unsigned w) { return __uint_as_float(w << 16); }
; __device__ __forceinline__ float bf_hi(unsigned w) { return __uint_as_float(w & 0xffff0000u); }
; #define PG8_STAGE(bufoff, gbase, voff) do { _Pragma("unroll") for (int _i = 0; _i < 2; ++_i) \
;         __builtin_amdgcn_global_load_lds((const unsigned*)((const char*)(gbase) + (voff)[_i]), (LAS unsigned*)(lds + (bufoff) + ldsw + _i * 8192), 16, 0, 0); } while (0)
; #define PG8_WAIT_V(n) asm volatile("s_waitcnt vmcnt(" #n ")" ::: "memory")
; #define PG8_WAIT_L(n) asm volatile("s_waitcnt lgkmcnt(" #n ")" ::: "memory")
; #define PG8_BAR __builtin_amdgcn_s_barrier()
; #define PG8_SCHED __builtin_amdgcn_sched_barrier(0)
; template <class Epi, class Ptrs>
; __device__ __forceinline__ void gemm_phase(LAS unsigned char* lds, const int K, const StaticOrder& S, const Ptrs& P, const Epi& E) {
;     ...
;             PG8_BAR; PG8_WAIT_L(0); PG8_MMA(1, 0, At, B0); PG8_BAR; PG8_SCHED;
;             PG8_STAGE(PG8_SB(1, 1), b3 + hstep, voffB);
;             PG8_WAIT_V(6); PG8_BAR; PG8_MMA(1, 1, At, B1); PG8_BAR;
;     __device__ __forceinline__ void operator()(const f32x4 (&acc)[2][2][4][2], const Unit& u, int ui, int wr, int wc, int fr, int fq) const {
;         const int rl0 = wr * 64 + fr, col0 = u.pn * 256 + wc * 32 + 8 * fq;
;         u32x4 xv[2][4][2];
; #pragma unroll
;         for (int ai = 0; ai < 2; ++ai)
; #pragma unroll
;             for (int m = 0; m < 4; ++m)
; #pragma unroll
;                 for (int bj = 0; bj < 2; ++bj) xv[ai][m][bj] = *(const u32x4*)(xb + (size_t)(u.pm * 256 + rl0 + ai * 128 + m * 16) * DM + col0 + bj * 128);
; #pragma unroll
;         for (int ai = 0; ai < 2; ++ai)
; #pragma unroll
;             for (int m = 0; m < 4; ++m) { const int rl = rl0 + ai * 128 + m * 16; float* rowp = out + (size_t)(u.pm * 256 + rl) * DM + col0;
;                 const float r2 = tab[ui * 256 + rl];
; #pragma unroll
;                 for (int bj = 0; bj < 2; ++bj) { const u32x4 x = xv[ai][m][bj];
;                     const f32x4 x0 = {bf_lo(x.x), bf_hi(x.x), bf_lo(x.y), bf_hi(x.y)}, x1 = {bf_lo(x.z), bf_hi(x.z), bf_lo(x.w), bf_hi(x.w)};
;                     *(f32x4*)(rowp + bj * 128) = acc[ai][bj][m][0] * r2 + x0; *(f32x4*)(rowp + bj * 128 + 4) = acc[ai][bj][m][1] * r2 + x1; } }
	s_waitcnt lgkmcnt(0)
	s_waitcnt lgkmcnt(0)
	v_mfma_f32_16x16x32_bf16 v[60:63], v[128:131], v[144:147], v[60:63]
	v_mfma_f32_16x16x32_bf16 v[60:63], v[132:135], v[148:151], v[60:63]
	v_mfma_f32_16x16x32_bf16 v[56:59], v[140:143], v[148:151], v[56:59]
	v_mfma_f32_16x16x32_bf16 v[56:59], v[136:139], v[144:147], v[56:59]
	v_mfma_f32_16x16x32_bf16 v[40:43], v[136:139], v[152:155], v[40:43]
	v_mfma_f32_16x16x32_bf16 v[40:43], v[140:143], v[156:159], v[40:43]
	v_mfma_f32_16x16x32_bf16 v[48:51], v[132:135], v[156:159], v[48:51]
	v_mfma_f32_16x16x32_bf16 v[48:51], v[128:131], v[152:155], v[48:51]
	v_mfma_f32_16x16x32_bf16 v[32:35], v[128:131], v[176:179], v[32:35]
	v_mfma_f32_16x16x32_bf16 v[32:35], v[132:135], v[180:183], v[32:35]
	v_mfma_f32_16x16x32_bf16 v[24:27], v[140:143], v[180:183], v[24:27]
	v_mfma_f32_16x16x32_bf16 v[24:27], v[136:139], v[176:179], v[24:27]
	v_mfma_f32_16x16x32_bf16 v[8:11], v[136:139], v[196:199], v[8:11]
	v_mfma_f32_16x16x32_bf16 v[8:11], v[140:143], v[200:203], v[8:11]
	v_mfma_f32_16x16x32_bf16 v[16:19], v[132:135], v[200:203], v[16:19]
	v_mfma_f32_16x16x32_bf16 v[16:19], v[128:131], v[196:199], v[16:19]
	s_barrier
	s_add_u32 s22, s22, 0x100080
	s_addc_u32 s23, s23, 0
	s_add_i32 s24, s24, s34
	s_mov_b32 m0, s24
	s_nop 0
	global_load_lds_dwordx4 v162, s[22:23]
	s_add_i32 m0, s24, 0x2000
	s_nop 0
	global_load_lds_dwordx4 v166, s[22:23]
	s_waitcnt vmcnt(6)
	s_barrier
	v_mfma_f32_16x16x32_bf16 v[52:55], v[204:207], v[144:147], v[52:55]
	v_mfma_f32_16x16x32_bf16 v[52:55], v[208:211], v[148:151], v[52:55]
	v_mfma_f32_16x16x32_bf16 v[44:47], v[216:219], v[148:151], v[44:47]
	v_mfma_f32_16x16x32_bf16 v[44:47], v[212:215], v[144:147], v[44:47]
	v_mfma_f32_16x16x32_bf16 v[28:31], v[212:215], v[152:155], v[28:31]
	v_mfma_f32_16x16x32_bf16 v[28:31], v[216:219], v[156:159], v[28:31]
	v_mfma_f32_16x16x32_bf16 v[36:39], v[208:211], v[156:159], v[36:39]
	v_mfma_f32_16x16x32_bf16 v[36:39], v[204:207], v[152:155], v[36:39]
	v_mfma_f32_16x16x32_bf16 v[20:23], v[204:207], v[176:179], v[20:23]
	v_mfma_f32_16x16x32_bf16 v[20:23], v[208:211], v[180:183], v[20:23]
	v_mfma_f32_16x16x32_bf16 v[12:15], v[216:219], v[180:183], v[12:15]
	v_mfma_f32_16x16x32_bf16 v[12:15], v[212:215], v[176:179], v[12:15]
	v_mfma_f32_16x16x32_bf16 v[0:3], v[212:215], v[196:199], v[0:3]
	v_mfma_f32_16x16x32_bf16 v[0:3], v[216:219], v[200:203], v[0:3]
	v_mfma_f32_16x16x32_bf16 v[4:7], v[208:211], v[200:203], v[4:7]
	v_mfma_f32_16x16x32_bf16 v[4:7], v[204:207], v[196:199], v[4:7]
	s_add_i32 s46, s46, 2
	s_add_u32 s20, s20, 0x100
	s_addc_u32 s21, s21, 0
	s_add_u32 s11, s11, 0x100
	s_addc_u32 s13, s13, 0
	s_cmp_gt_u32 s46, 61
	s_barrier
	s_cbranch_scc0 .LBB0_522
	s_nop 0
	s_nop 0
	s_nop 0
	s_nop 0
	s_nop 0
	s_nop 0
	s_nop 0
	s_nop 0
	s_nop 0
	s_nop 0
	s_nop 0
	s_nop 0
	s_nop 0
	s_nop 0
	s_nop 0
	s_nop 0
	s_nop 0
	s_nop 0
	s_nop 0
	s_nop 0
	s_nop 0
	s_nop 0
	s_nop 0
	s_nop 0
	s_nop 0
	s_nop 0
	s_nop 0
	s_nop 0
	s_nop 0
	s_nop 0
	s_nop 0
	s_nop 0
	s_lshl_b32 s11, s18, 8
	v_lshl_or_b32 v128, s16, 8, v191
	v_add_u32_e32 v130, s11, v186
	v_ashrrev_i32_e32 v129, 31, v128
	v_ashrrev_i32_e32 v131, 31, v130
	v_lshl_add_u64 v[132:133], v[128:129], 1, s[6:7]
	v_lshlrev_b64 v[134:135], 11, v[130:131]
	v_lshl_add_u64 v[134:135], v[132:133], 0, v[134:135]
	global_load_dwordx4 v[198:201], v[134:135], off
	global_load_dwordx4 v[202:205], v[134:135], off offset:256
	v_or_b32_e32 v134, 16, v130
	v_ashrrev_i32_e32 v135, 31, v134
	v_lshlrev_b64 v[134:135], 11, v[134:135]
	v_lshl_add_u64 v[134:135], v[132:133], 0, v[134:135]
	global_load_dwordx4 v[206:209], v[134:135], off
	global_load_dwordx4 v[210:213], v[134:135], off offset:256
	v_or_b32_e32 v136, 32, v130
	v_ashrrev_i32_e32 v137, 31, v136
	v_or_b32_e32 v138, 48, v130
	v_add_u32_e32 v184, 0x80, v130
	v_add_u32_e32 v182, 0x90, v130
	v_add_u32_e32 v180, 0xa0, v130
	v_add_u32_e32 v178, 0xb0, v130
	v_lshlrev_b64 v[176:177], 2, v[128:129]
	v_lshlrev_b64 v[128:129], 12, v[130:131]
	v_lshlrev_b64 v[130:131], 11, v[136:137]
	v_lshl_add_u64 v[130:131], v[132:133], 0, v[130:131]
	global_load_dwordx4 v[214:217], v[130:131], off
	v_ashrrev_i32_e32 v139, 31, v138
	v_ashrrev_i32_e32 v185, 31, v184
	v_ashrrev_i32_e32 v183, 31, v182
	v_ashrrev_i32_e32 v181, 31, v180
	v_ashrrev_i32_e32 v179, 31, v178
	v_lshlrev_b64 v[134:135], 11, v[138:139]
	v_lshlrev_b64 v[136:137], 11, v[184:185]
	v_lshlrev_b64 v[138:139], 11, v[182:183]
	v_lshl_add_u32 v196, s45, 10, v192
	v_lshlrev_b64 v[140:141], 11, v[180:181]
	v_lshlrev_b64 v[142:143], 11, v[178:179]
	v_lshl_add_u64 v[128:129], s[26:27], 0, v[128:129]
	v_lshl_add_u64 v[134:135], v[132:133], 0, v[134:135]
	v_lshl_add_u64 v[136:137], v[132:133], 0, v[136:137]
	v_lshl_add_u64 v[138:139], v[132:133], 0, v[138:139]
	ds_read2_b32 v[230:231], v196 offset1:16
	v_lshl_add_u64 v[234:235], v[132:133], 0, v[140:141]
	v_lshl_add_u64 v[236:237], v[132:133], 0, v[142:143]
	v_lshl_add_u64 v[238:239], v[128:129], 0, v[176:177]
	global_load_dwordx4 v[218:221], v[130:131], off offset:256
	global_load_dwordx4 v[222:225], v[134:135], off
	global_load_dwordx4 v[226:229], v[134:135], off offset:256
	global_load_dwordx4 v[156:159], v[136:137], off
	global_load_dwordx4 v[152:155], v[136:137], off offset:256
	global_load_dwordx4 v[148:151], v[138:139], off
	global_load_dwordx4 v[144:147], v[138:139], off offset:256
	global_load_dwordx4 v[140:143], v[234:235], off
	s_nop 0
	global_load_dwordx4 v[136:139], v[234:235], off offset:256
	global_load_dwordx4 v[132:135], v[236:237], off
	global_load_dwordx4 v[128:131], v[236:237], off offset:256
	v_add_u32_e32 v232, s11, v188
	v_ashrrev_i32_e32 v233, 31, v232
	s_and_b64 vcc, exec, s[0:1]
	s_mov_b32 s16, s10
	s_mov_b32 s18, s12
	s_mov_b64 s[20:21], s[4:5]
	s_mov_b64 s[22:23], s[14:15]
	s_mov_b32 s45, s44
	s_waitcnt vmcnt(0)
; __device__ __forceinline__ float bf_lo(unsigned w) { return __uint_as_float(w << 16); }
; __device__ __forceinline__ float bf_hi(unsigned w) { return __uint_as_float(w & 0xffff0000u); }
;     __device__ __forceinline__ void operator()(const f32x4 (&acc)[2][2][4][2], const Unit& u, int ui, int wr, int wc, int fr, int fq) const {
;     ...
;         for (int ai = 0; ai < 2; ++ai)
; #pragma unroll
;             for (int m = 0; m < 4; ++m) { const int rl = rl0 + ai * 128 + m * 16; float* rowp = out + (size_t)(u.pm * 256 + rl) * DM + col0;
;                 const float r2 = tab[ui * 256 + rl];
; #pragma unroll
;                 for (int bj = 0; bj < 2; ++bj) { const u32x4 x = xv[ai][m][bj];
;                     const f32x4 x0 = {bf_lo(x.x), bf_hi(x.x), bf_lo(x.y), bf_hi(x.y)}, x1 = {bf_lo(x.z), bf_hi(x.z), bf_lo(x.w), bf_hi(x.w)};
;                     *(f32x4*)(rowp + bj * 128) = acc[ai][bj][m][0] * r2 + x0; *(f32x4*)(rowp + bj * 128 + 4) = acc[ai][bj][m][1] * r2 + x1; } }
	v_lshlrev_b32_e32 v234, 16, v198
	v_and_b32_e32 v235, 0xffff0000, v198
	v_lshlrev_b32_e32 v198, 16, v199
	v_and_b32_e32 v199, 0xffff0000, v199
	v_lshlrev_b32_e32 v242, 16, v204
	v_and_b32_e32 v243, 0xffff0000, v204
	v_lshlrev_b32_e32 v236, 16, v200
	v_and_b32_e32 v237, 0xffff0000, v200
	v_lshlrev_b32_e32 v200, 16, v201
	v_and_b32_e32 v201, 0xffff0000, v201
	v_lshlrev_b32_e32 v240, 16, v202
	v_and_b32_e32 v241, 0xffff0000, v202
	v_lshlrev_b32_e32 v202, 16, v203
	v_and_b32_e32 v203, 0xffff0000, v203
	v_lshlrev_b32_e32 v204, 16, v205
	v_and_b32_e32 v205, 0xffff0000, v205
	s_waitcnt lgkmcnt(0)
	v_pk_fma_f32 v[126:127], v[126:127], v[230:231], v[198:199] op_sel_hi:[1,0,1]
	v_pk_fma_f32 v[124:125], v[124:125], v[230:231], v[234:235] op_sel_hi:[1,0,1]
	v_pk_fma_f32 v[108:109], v[108:109], v[230:231], v[242:243] op_sel_hi:[1,0,1]
	v_pk_fma_f32 v[122:123], v[122:123], v[230:231], v[200:201] op_sel_hi:[1,0,1]
	v_pk_fma_f32 v[120:121], v[120:121], v[230:231], v[236:237] op_sel_hi:[1,0,1]
	v_pk_fma_f32 v[118:119], v[118:119], v[230:231], v[202:203] op_sel_hi:[1,0,1]
	v_pk_fma_f32 v[116:117], v[116:117], v[230:231], v[240:241] op_sel_hi:[1,0,1]
	v_pk_fma_f32 v[110:111], v[110:111], v[230:231], v[204:205] op_sel_hi:[1,0,1]
	global_store_dwordx4 v[238:239], v[124:127], off
	global_store_dwordx4 v[238:239], v[120:123], off offset:16
	global_store_dwordx4 v[238:239], v[116:119], off offset:512
	global_store_dwordx4 v[238:239], v[108:111], off offset:528
	v_mov_b32_e32 v122, v231
	v_lshlrev_b32_e32 v118, 16, v208
	v_lshlrev_b64 v[108:109], 12, v[232:233]
	v_lshl_add_u64 v[108:109], s[26:27], 0, v[108:109]
	v_lshl_add_u64 v[116:117], v[108:109], 0, v[176:177]
	v_lshlrev_b32_e32 v108, 16, v206
	v_and_b32_e32 v109, 0xffff0000, v206
	v_lshlrev_b32_e32 v110, 16, v207
	v_and_b32_e32 v111, 0xffff0000, v207
	v_pk_fma_f32 v[110:111], v[114:115], v[122:123], v[110:111] op_sel_hi:[1,0,1]
	v_pk_fma_f32 v[108:109], v[112:113], v[122:123], v[108:109] op_sel_hi:[1,0,1]
	global_store_dwordx4 v[116:117], v[108:111], off
	v_and_b32_e32 v119, 0xffff0000, v208
	v_lshlrev_b32_e32 v120, 16, v209
	v_lshlrev_b32_e32 v108, 16, v212
	v_and_b32_e32 v109, 0xffff0000, v212
	v_lshlrev_b32_e32 v110, 16, v213
	v_and_b32_e32 v111, 0xffff0000, v213
	v_pk_fma_f32 v[98:99], v[98:99], v[122:123], v[110:111] op_sel_hi:[1,0,1]
	v_pk_fma_f32 v[96:97], v[96:97], v[122:123], v[108:109] op_sel_hi:[1,0,1]
	v_and_b32_e32 v121, 0xffff0000, v209
	global_store_dwordx4 v[116:117], v[96:99], off offset:528
	ds_read2_b32 v[98:99], v196 offset0:32 offset1:48
	v_pk_fma_f32 v[106:107], v[106:107], v[122:123], v[120:121] op_sel_hi:[1,0,1]
	v_pk_fma_f32 v[104:105], v[104:105], v[122:123], v[118:119] op_sel_hi:[1,0,1]
	v_add_u32_e32 v96, s11, v189
	global_store_dwordx4 v[116:117], v[104:107], off offset:16
	v_ashrrev_i32_e32 v97, 31, v96
	v_lshlrev_b64 v[96:97], 12, v[96:97]
	v_lshlrev_b32_e32 v104, 16, v210
	v_and_b32_e32 v105, 0xffff0000, v210
	v_lshlrev_b32_e32 v106, 16, v211
	v_and_b32_e32 v107, 0xffff0000, v211
	v_pk_fma_f32 v[102:103], v[102:103], v[122:123], v[106:107] op_sel_hi:[1,0,1]
	v_pk_fma_f32 v[100:101], v[100:101], v[122:123], v[104:105] op_sel_hi:[1,0,1]
	global_store_dwordx4 v[116:117], v[100:103], off offset:512
	v_lshl_add_u64 v[96:97], s[26:27], 0, v[96:97]
	v_lshl_add_u64 v[96:97], v[96:97], 0, v[176:177]
	v_lshlrev_b32_e32 v100, 16, v214
	v_and_b32_e32 v101, 0xffff0000, v214
	v_lshlrev_b32_e32 v102, 16, v215
	v_and_b32_e32 v103, 0xffff0000, v215
	s_waitcnt lgkmcnt(0)
	v_pk_fma_f32 v[94:95], v[94:95], v[98:99], v[102:103] op_sel_hi:[1,0,1]
	v_pk_fma_f32 v[92:93], v[92:93], v[98:99], v[100:101] op_sel_hi:[1,0,1]
	global_store_dwordx4 v[96:97], v[92:95], off
	v_lshlrev_b32_e32 v104, 16, v216
	v_and_b32_e32 v105, 0xffff0000, v216
	v_lshlrev_b32_e32 v92, 16, v220
	v_and_b32_e32 v93, 0xffff0000, v220
	v_lshlrev_b32_e32 v94, 16, v221
	v_and_b32_e32 v95, 0xffff0000, v221
	v_lshlrev_b32_e32 v106, 16, v217
	v_and_b32_e32 v107, 0xffff0000, v217
	v_pk_fma_f32 v[82:83], v[82:83], v[98:99], v[94:95] op_sel_hi:[1,0,1]
	v_pk_fma_f32 v[80:81], v[80:81], v[98:99], v[92:93] op_sel_hi:[1,0,1]
	v_pk_fma_f32 v[90:91], v[90:91], v[98:99], v[106:107] op_sel_hi:[1,0,1]
	v_pk_fma_f32 v[88:89], v[88:89], v[98:99], v[104:105] op_sel_hi:[1,0,1]
	global_store_dwordx4 v[96:97], v[80:83], off offset:528
	global_store_dwordx4 v[96:97], v[88:91], off offset:16
	s_nop 0
	v_add_u32_e32 v80, s11, v190
	v_lshlrev_b32_e32 v88, 16, v218
	v_and_b32_e32 v89, 0xffff0000, v218
	v_lshlrev_b32_e32 v90, 16, v219
	v_and_b32_e32 v91, 0xffff0000, v219
	v_ashrrev_i32_e32 v81, 31, v80
	v_pk_fma_f32 v[86:87], v[86:87], v[98:99], v[90:91] op_sel_hi:[1,0,1]
	v_pk_fma_f32 v[84:85], v[84:85], v[98:99], v[88:89] op_sel_hi:[1,0,1]
	v_lshlrev_b64 v[80:81], 12, v[80:81]
	global_store_dwordx4 v[96:97], v[84:87], off offset:512
	v_lshl_add_u64 v[80:81], s[26:27], 0, v[80:81]
	v_lshlrev_b32_e32 v82, 16, v222
	v_and_b32_e32 v83, 0xffff0000, v222
	v_lshlrev_b32_e32 v84, 16, v223
	v_and_b32_e32 v85, 0xffff0000, v223
	v_mov_b32_e32 v90, v99
	v_lshl_add_u64 v[80:81], v[80:81], 0, v[176:177]
	v_pk_fma_f32 v[78:79], v[78:79], v[90:91], v[84:85] op_sel_hi:[1,0,1]
	v_pk_fma_f32 v[76:77], v[76:77], v[90:91], v[82:83] op_sel_hi:[1,0,1]
	global_store_dwordx4 v[80:81], v[76:79], off
	v_lshlrev_b32_e32 v86, 16, v224
	v_and_b32_e32 v87, 0xffff0000, v224
	v_lshlrev_b32_e32 v76, 16, v228
	v_and_b32_e32 v77, 0xffff0000, v228
	v_lshlrev_b32_e32 v78, 16, v229
	v_and_b32_e32 v79, 0xffff0000, v229
	v_pk_fma_f32 v[66:67], v[66:67], v[90:91], v[78:79] op_sel_hi:[1,0,1]
	v_pk_fma_f32 v[64:65], v[64:65], v[90:91], v[76:77] op_sel_hi:[1,0,1]
	v_lshlrev_b32_e32 v88, 16, v225
	v_and_b32_e32 v89, 0xffff0000, v225
	global_store_dwordx4 v[80:81], v[64:67], off offset:528
	ds_read2_b32 v[66:67], v196 offset0:128 offset1:144
	v_pk_fma_f32 v[74:75], v[74:75], v[90:91], v[88:89] op_sel_hi:[1,0,1]
	v_pk_fma_f32 v[72:73], v[72:73], v[90:91], v[86:87] op_sel_hi:[1,0,1]
	global_store_dwordx4 v[80:81], v[72:75], off offset:16
	v_lshlrev_b64 v[64:65], 12, v[184:185]
	v_lshl_add_u64 v[64:65], s[26:27], 0, v[64:65]
	v_lshlrev_b32_e32 v72, 16, v226
	v_and_b32_e32 v73, 0xffff0000, v226
	v_lshlrev_b32_e32 v74, 16, v227
	v_and_b32_e32 v75, 0xffff0000, v227
	v_pk_fma_f32 v[70:71], v[70:71], v[90:91], v[74:75] op_sel_hi:[1,0,1]
	v_pk_fma_f32 v[68:69], v[68:69], v[90:91], v[72:73] op_sel_hi:[1,0,1]
	global_store_dwordx4 v[80:81], v[68:71], off offset:512
	v_lshl_add_u64 v[64:65], v[64:65], 0, v[176:177]
	v_lshlrev_b32_e32 v72, 16, v158
	v_lshlrev_b32_e32 v68, 16, v156
	v_and_b32_e32 v69, 0xffff0000, v156
	v_lshlrev_b32_e32 v70, 16, v157
	v_and_b32_e32 v71, 0xffff0000, v157
	v_and_b32_e32 v73, 0xffff0000, v158
	v_lshlrev_b32_e32 v74, 16, v159
	v_and_b32_e32 v75, 0xffff0000, v159
	s_waitcnt lgkmcnt(0)
; __device__ __forceinline__ float bf_lo(unsigned w) { return __uint_as_float(w << 16); }
; __device__ __forceinline__ float bf_hi(unsigned w) { return __uint_as_float(w & 0xffff0000u); }
; #define PG8_WAIT_V(n) asm volatile("s_waitcnt vmcnt(" #n ")" ::: "memory")
; #define PG8_BAR __builtin_amdgcn_s_barrier()
; template <class Epi, class Ptrs>
; __device__ __forceinline__ void gemm_phase(LAS unsigned char* lds, const int K, const StaticOrder& S, const Ptrs& P, const Epi& E) {
;     ...
;     PG8_WAIT_V(0);
;     if (wr == 0) PG8_BAR;
;     __device__ __forceinline__ void operator()(const f32x4 (&acc)[2][2][4][2], const Unit& u, int ui, int wr, int wc, int fr, int fq) const {
;     ...
;             for (int m = 0; m < 4; ++m) { const int rl = rl0 + ai * 128 + m * 16; float* rowp = out + (size_t)(u.pm * 256 + rl) * DM + col0;
;                 const float r2 = tab[ui * 256 + rl];
; #pragma unroll
;                 for (int bj = 0; bj < 2; ++bj) { const u32x4 x = xv[ai][m][bj];
;                     const f32x4 x0 = {bf_lo(x.x), bf_hi(x.x), bf_lo(x.y), bf_hi(x.y)}, x1 = {bf_lo(x.z), bf_hi(x.z), bf_lo(x.w), bf_hi(x.w)};
;                     *(f32x4*)(rowp + bj * 128) = acc[ai][bj][m][0] * r2 + x0; *(f32x4*)(rowp + bj * 128 + 4) = acc[ai][bj][m][1] * r2 + x1; } }
	v_pk_fma_f32 v[62:63], v[62:63], v[66:67], v[70:71] op_sel_hi:[1,0,1]
	v_pk_fma_f32 v[60:61], v[60:61], v[66:67], v[68:69] op_sel_hi:[1,0,1]
	global_store_dwordx4 v[64:65], v[60:63], off
	v_pk_fma_f32 v[58:59], v[58:59], v[66:67], v[74:75] op_sel_hi:[1,0,1]
	v_pk_fma_f32 v[56:57], v[56:57], v[66:67], v[72:73] op_sel_hi:[1,0,1]
	v_lshlrev_b32_e32 v60, 16, v154
	v_and_b32_e32 v61, 0xffff0000, v154
	v_lshlrev_b32_e32 v62, 16, v155
	v_and_b32_e32 v63, 0xffff0000, v155
	global_store_dwordx4 v[64:65], v[56:59], off offset:16
	v_pk_fma_f32 v[46:47], v[46:47], v[66:67], v[62:63] op_sel_hi:[1,0,1]
	v_pk_fma_f32 v[44:45], v[44:45], v[66:67], v[60:61] op_sel_hi:[1,0,1]
	v_lshlrev_b32_e32 v56, 16, v152
	v_and_b32_e32 v57, 0xffff0000, v152
	v_lshlrev_b32_e32 v58, 16, v153
	v_and_b32_e32 v59, 0xffff0000, v153
	v_pk_fma_f32 v[54:55], v[54:55], v[66:67], v[58:59] op_sel_hi:[1,0,1]
	v_pk_fma_f32 v[52:53], v[52:53], v[66:67], v[56:57] op_sel_hi:[1,0,1]
	global_store_dwordx4 v[64:65], v[44:47], off offset:528
	global_store_dwordx4 v[64:65], v[52:55], off offset:512
	v_lshlrev_b32_e32 v56, 16, v151
	v_lshlrev_b64 v[44:45], 12, v[182:183]
	v_lshl_add_u64 v[44:45], s[26:27], 0, v[44:45]
	v_lshlrev_b32_e32 v54, 16, v150
	v_and_b32_e32 v55, 0xffff0000, v150
	v_and_b32_e32 v57, 0xffff0000, v151
	v_mov_b32_e32 v58, v67
	v_lshl_add_u64 v[52:53], v[44:45], 0, v[176:177]
	v_pk_fma_f32 v[42:43], v[42:43], v[58:59], v[56:57] op_sel_hi:[1,0,1]
	v_pk_fma_f32 v[40:41], v[40:41], v[58:59], v[54:55] op_sel_hi:[1,0,1]
	v_lshlrev_b32_e32 v44, 16, v148
	v_and_b32_e32 v45, 0xffff0000, v148
	v_lshlrev_b32_e32 v46, 16, v149
	v_and_b32_e32 v47, 0xffff0000, v149
	global_store_dwordx4 v[52:53], v[40:43], off offset:16
	v_pk_fma_f32 v[46:47], v[50:51], v[58:59], v[46:47] op_sel_hi:[1,0,1]
	v_pk_fma_f32 v[44:45], v[48:49], v[58:59], v[44:45] op_sel_hi:[1,0,1]
	v_lshlrev_b32_e32 v40, 16, v144
	v_and_b32_e32 v41, 0xffff0000, v144
	v_lshlrev_b32_e32 v42, 16, v145
	v_and_b32_e32 v43, 0xffff0000, v145
	v_pk_fma_f32 v[38:39], v[38:39], v[58:59], v[42:43] op_sel_hi:[1,0,1]
	v_pk_fma_f32 v[36:37], v[36:37], v[58:59], v[40:41] op_sel_hi:[1,0,1]
	global_store_dwordx4 v[52:53], v[44:47], off
	global_store_dwordx4 v[52:53], v[36:39], off offset:512
	ds_read2_b32 v[38:39], v196 offset0:160 offset1:176
	v_lshlrev_b32_e32 v44, 16, v146
	v_and_b32_e32 v45, 0xffff0000, v146
	v_lshlrev_b32_e32 v46, 16, v147
	v_and_b32_e32 v47, 0xffff0000, v147
	v_pk_fma_f32 v[30:31], v[30:31], v[58:59], v[46:47] op_sel_hi:[1,0,1]
	v_pk_fma_f32 v[28:29], v[28:29], v[58:59], v[44:45] op_sel_hi:[1,0,1]
	global_store_dwordx4 v[52:53], v[28:31], off offset:528
	v_lshlrev_b32_e32 v40, 16, v142
	v_and_b32_e32 v41, 0xffff0000, v142
	v_lshlrev_b64 v[28:29], 12, v[180:181]
	v_lshl_add_u64 v[28:29], s[26:27], 0, v[28:29]
	v_lshl_add_u64 v[36:37], v[28:29], 0, v[176:177]
	v_lshlrev_b32_e32 v28, 16, v140
	v_and_b32_e32 v29, 0xffff0000, v140
	v_lshlrev_b32_e32 v30, 16, v141
	v_and_b32_e32 v31, 0xffff0000, v141
	s_waitcnt lgkmcnt(0)
	v_pk_fma_f32 v[30:31], v[34:35], v[38:39], v[30:31] op_sel_hi:[1,0,1]
	v_pk_fma_f32 v[28:29], v[32:33], v[38:39], v[28:29] op_sel_hi:[1,0,1]
	v_lshlrev_b32_e32 v42, 16, v143
	v_and_b32_e32 v43, 0xffff0000, v143
	global_store_dwordx4 v[36:37], v[28:31], off
	v_pk_fma_f32 v[26:27], v[26:27], v[38:39], v[42:43] op_sel_hi:[1,0,1]
	v_pk_fma_f32 v[24:25], v[24:25], v[38:39], v[40:41] op_sel_hi:[1,0,1]
	v_lshlrev_b32_e32 v28, 16, v138
	v_and_b32_e32 v29, 0xffff0000, v138
	v_lshlrev_b32_e32 v30, 16, v139
	v_and_b32_e32 v31, 0xffff0000, v139
	v_pk_fma_f32 v[14:15], v[14:15], v[38:39], v[30:31] op_sel_hi:[1,0,1]
	v_pk_fma_f32 v[12:13], v[12:13], v[38:39], v[28:29] op_sel_hi:[1,0,1]
	global_store_dwordx4 v[36:37], v[24:27], off offset:16
	global_store_dwordx4 v[36:37], v[12:15], off offset:528
	s_nop 0
	v_lshlrev_b32_e32 v24, 16, v136
	v_and_b32_e32 v25, 0xffff0000, v136
	v_lshlrev_b32_e32 v26, 16, v137
	v_and_b32_e32 v27, 0xffff0000, v137
	v_lshlrev_b64 v[12:13], 12, v[178:179]
	v_pk_fma_f32 v[22:23], v[22:23], v[38:39], v[26:27] op_sel_hi:[1,0,1]
	v_pk_fma_f32 v[20:21], v[20:21], v[38:39], v[24:25] op_sel_hi:[1,0,1]
	v_lshl_add_u64 v[12:13], s[26:27], 0, v[12:13]
	global_store_dwordx4 v[36:37], v[20:23], off offset:512
	v_lshlrev_b32_e32 v14, 16, v133
	v_and_b32_e32 v15, 0xffff0000, v133
	v_lshl_add_u64 v[20:21], v[12:13], 0, v[176:177]
	v_lshlrev_b32_e32 v12, 16, v132
	v_and_b32_e32 v13, 0xffff0000, v132
	v_lshlrev_b32_e32 v22, 16, v134
	v_and_b32_e32 v23, 0xffff0000, v134
	v_lshlrev_b32_e32 v24, 16, v135
	v_and_b32_e32 v25, 0xffff0000, v135
	v_mov_b32_e32 v26, v39
	v_pk_fma_f32 v[14:15], v[18:19], v[26:27], v[14:15] op_sel_hi:[1,0,1]
	v_pk_fma_f32 v[12:13], v[16:17], v[26:27], v[12:13] op_sel_hi:[1,0,1]
	v_pk_fma_f32 v[10:11], v[10:11], v[26:27], v[24:25] op_sel_hi:[1,0,1]
	v_pk_fma_f32 v[8:9], v[8:9], v[26:27], v[22:23] op_sel_hi:[1,0,1]
	global_store_dwordx4 v[20:21], v[12:15], off
	global_store_dwordx4 v[20:21], v[8:11], off offset:16
	s_nop 0
	v_lshlrev_b32_e32 v12, 16, v130
	v_lshlrev_b32_e32 v8, 16, v128
	v_and_b32_e32 v9, 0xffff0000, v128
	v_lshlrev_b32_e32 v10, 16, v129
	v_and_b32_e32 v11, 0xffff0000, v129
	v_and_b32_e32 v13, 0xffff0000, v130
	v_lshlrev_b32_e32 v14, 16, v131
	v_and_b32_e32 v15, 0xffff0000, v131
	v_pk_fma_f32 v[6:7], v[6:7], v[26:27], v[10:11] op_sel_hi:[1,0,1]
	v_pk_fma_f32 v[4:5], v[4:5], v[26:27], v[8:9] op_sel_hi:[1,0,1]
	v_pk_fma_f32 v[2:3], v[2:3], v[26:27], v[14:15] op_sel_hi:[1,0,1]
	v_pk_fma_f32 v[0:1], v[0:1], v[26:27], v[12:13] op_sel_hi:[1,0,1]
	global_store_dwordx4 v[20:21], v[4:7], off offset:512
	global_store_dwordx4 v[20:21], v[0:3], off offset:528
	s_cbranch_vccz .LBB0_517
	s_waitcnt vmcnt(0)
	s_cmpk_gt_u32 s33, 0xff
	s_cbranch_scc1 .LBB0_526
	s_barrier
